# hyena: hand-written scalar-f32 radix-4 inverse middle passes (LQ 2..10)
# speedup vs baseline: 1.0208x; 1.0073x over previous
; HD float2 cmul(float2 a, float2 b){ return make_float2(a.x*b.x - a.y*b.y, a.x*b.y + a.y*b.x); }
; HD float2 cmulc(float2 a, float2 b){ return make_float2(a.x*b.x + a.y*b.y, a.y*b.x - a.x*b.y); }
; template<bool INV, bool NOTW>
; HD void bf4c(float2* Z, int i0, int i1, int i2, int i3, float2 w1, float2 w2, float2 w3){
;   float2 a0=Z[i0], a1=Z[i1], a2=Z[i2], a3=Z[i3];
;   if (INV && !NOTW){ a1=cmulc(a1,w1); a2=cmulc(a2,w2); a3=cmulc(a3,w3); }
;   float2 s02=make_float2(a0.x+a2.x,a0.y+a2.y), d02=make_float2(a0.x-a2.x,a0.y-a2.y);
;   float2 s13=make_float2(a1.x+a3.x,a1.y+a3.y), d13=make_float2(a1.x-a3.x,a1.y-a3.y);
;   float2 y0=make_float2(s02.x+s13.x,s02.y+s13.y), y2=make_float2(s02.x-s13.x,s02.y-s13.y);
;   float2 ym=make_float2(d02.x+d13.y,d02.y-d13.x);
;   float2 yp=make_float2(d02.x-d13.y,d02.y+d13.x);
;   float2 y1, y3;
;   if (INV){ y1=yp; y3=ym; } else if (NOTW){ y1=ym; y3=yp; } else { y1=cmul(ym,w1); y2=cmul(y2,w2); y3=cmul(yp,w3); }
;   Z[i0]=y0; Z[i1]=y1; Z[i2]=y2; Z[i3]=y3;
; }
; template<bool INV, int LQ, bool BARRIER=true>
; HD void fft_pass(float2* Z, const float2* twA, const float2* twB, int tid){
;     ...
;   } else {
;     int j=tid&(q-1); int base0=((tid>>LQ)<<(LQ+2))+j;
;     float2 w1=make_float2(1.f,0.f), w2=w1, w3=w1;
;     if (LQ>0){ int k=j*tws; w1=cmul(twA[k>>6],twB[k&63]); w2=cmul(w1,w1); w3=cmul(w2,w1); }
;     _Pragma("unroll") for (int i=0;i<8;++i){ int base=base0+i*2048; bf4c<INV,(LQ==0)>(Z,base,base+q,base+2*q,base+3*q,w1,w2,w3); }
;   }
;   if (BARRIER) __syncthreads(); else asm volatile("s_waitcnt lgkmcnt(0)" ::: "memory");
.Lmy_pf_st1:
	global_load_dwordx4 v[228:231], v232, s[98:99]
	global_load_dwordx4 v[228:231], v233, s[98:99]
	global_load_dwordx4 v[228:231], v234, s[98:99]
	global_load_dwordx4 v[228:231], v235, s[98:99]
	s_add_u32 s98, s98, 0x1000000
	s_addc_u32 s99, s99, 0
	global_load_dwordx4 v[228:231], v232, s[98:99]
	global_load_dwordx4 v[228:231], v233, s[98:99]
	global_load_dwordx4 v[228:231], v234, s[98:99]
	global_load_dwordx4 v[228:231], v235, s[98:99]
	s_waitcnt lgkmcnt(0)
	v_and_b32_e32 v226, 3, v154
	v_lshlrev_b32_e32 v224, 7, v226
	v_add_u32_e32 v224, 0x20800, v224
	v_mov_b32_e32 v225, 0x20a00
	ds_read_b64 v[238:239], v224
	ds_read_b64 v[240:241], v225
	s_waitcnt lgkmcnt(0)
	v_mul_f32_e32 v227, v239, v241
	v_fma_f32 v16, v238, v240, -v227
	v_mul_f32_e32 v227, v239, v240
	v_fma_f32 v17, v238, v241, v227
	v_mul_f32_e32 v227, v17, v17
	v_fma_f32 v18, v16, v16, -v227
	v_mul_f32_e32 v227, v17, v16
	v_fma_f32 v19, v16, v17, v227
	v_mul_f32_e32 v227, v19, v17
	v_fma_f32 v20, v18, v16, -v227
	v_mul_f32_e32 v227, v19, v16
	v_fma_f32 v21, v18, v17, v227
	v_lshrrev_b32_e32 v222, 2, v154
	v_lshlrev_b32_e32 v222, 4, v222
	v_add_u32_e32 v222, v222, v226
	v_lshlrev_b32_e32 v222, 3, v222
	v_add_u32_e32 v223, 0x10000, v222
	ds_read_b64 v[0:1], v222 offset:0
	ds_read_b64 v[2:3], v222 offset:32
	ds_read_b64 v[4:5], v222 offset:64
	ds_read_b64 v[6:7], v222 offset:96
	ds_read_b64 v[8:9], v222 offset:16384
	ds_read_b64 v[10:11], v222 offset:16416
	ds_read_b64 v[12:13], v222 offset:16448
	ds_read_b64 v[14:15], v222 offset:16480
	s_waitcnt lgkmcnt(4)
	v_mul_f32_e32 v227, v3, v17
	v_fma_f32 v242, v2, v16, v227
	v_mul_f32_e32 v227, v2, v17
	v_fma_f32 v243, v3, v16, -v227
	v_mul_f32_e32 v227, v5, v19
	v_fma_f32 v244, v4, v18, v227
	v_mul_f32_e32 v227, v4, v19
	v_fma_f32 v245, v5, v18, -v227
	v_mul_f32_e32 v227, v7, v21
	v_fma_f32 v246, v6, v20, v227
	v_mul_f32_e32 v227, v6, v21
	v_fma_f32 v247, v7, v20, -v227
	v_add_f32_e32 v22, v0, v244
	v_sub_f32_e32 v24, v0, v244
	v_add_f32_e32 v26, v242, v246
	v_sub_f32_e32 v28, v242, v246
	v_add_f32_e32 v23, v1, v245
	v_sub_f32_e32 v25, v1, v245
	v_add_f32_e32 v27, v243, v247
	v_sub_f32_e32 v29, v243, v247
	v_add_f32_e32 v80, v22, v26
	v_add_f32_e32 v81, v23, v27
	ds_write_b64 v222, v[80:81] offset:0
	v_sub_f32_e32 v82, v24, v29
	v_add_f32_e32 v83, v25, v28
	ds_write_b64 v222, v[82:83] offset:32
	v_sub_f32_e32 v84, v22, v26
	v_sub_f32_e32 v85, v23, v27
	ds_write_b64 v222, v[84:85] offset:64
	v_add_f32_e32 v236, v24, v29
	v_sub_f32_e32 v237, v25, v28
	ds_write_b64 v222, v[236:237] offset:96
	ds_read_b64 v[0:1], v222 offset:32768
	ds_read_b64 v[2:3], v222 offset:32800
	ds_read_b64 v[4:5], v222 offset:32832
	ds_read_b64 v[6:7], v222 offset:32864
	s_waitcnt lgkmcnt(8)
	v_mul_f32_e32 v227, v11, v17
	v_fma_f32 v242, v10, v16, v227
	v_mul_f32_e32 v227, v10, v17
	v_fma_f32 v243, v11, v16, -v227
	v_mul_f32_e32 v227, v13, v19
	v_fma_f32 v244, v12, v18, v227
	v_mul_f32_e32 v227, v12, v19
	v_fma_f32 v245, v13, v18, -v227
	v_mul_f32_e32 v227, v15, v21
	v_fma_f32 v246, v14, v20, v227
	v_mul_f32_e32 v227, v14, v21
	v_fma_f32 v247, v15, v20, -v227
	v_add_f32_e32 v22, v8, v244
	v_sub_f32_e32 v24, v8, v244
	v_add_f32_e32 v26, v242, v246
	v_sub_f32_e32 v28, v242, v246
	v_add_f32_e32 v23, v9, v245
	v_sub_f32_e32 v25, v9, v245
	v_add_f32_e32 v27, v243, v247
	v_sub_f32_e32 v29, v243, v247
	v_add_f32_e32 v80, v22, v26
	v_add_f32_e32 v81, v23, v27
	ds_write_b64 v222, v[80:81] offset:16384
	v_sub_f32_e32 v82, v24, v29
	v_add_f32_e32 v83, v25, v28
	ds_write_b64 v222, v[82:83] offset:16416
	v_sub_f32_e32 v84, v22, v26
	v_sub_f32_e32 v85, v23, v27
	ds_write_b64 v222, v[84:85] offset:16448
	v_add_f32_e32 v236, v24, v29
	v_sub_f32_e32 v237, v25, v28
	ds_write_b64 v222, v[236:237] offset:16480
	ds_read_b64 v[8:9], v222 offset:49152
	ds_read_b64 v[10:11], v222 offset:49184
	ds_read_b64 v[12:13], v222 offset:49216
	ds_read_b64 v[14:15], v222 offset:49248
	s_waitcnt lgkmcnt(8)
	v_mul_f32_e32 v227, v3, v17
	v_fma_f32 v242, v2, v16, v227
	v_mul_f32_e32 v227, v2, v17
	v_fma_f32 v243, v3, v16, -v227
	v_mul_f32_e32 v227, v5, v19
	v_fma_f32 v244, v4, v18, v227
	v_mul_f32_e32 v227, v4, v19
	v_fma_f32 v245, v5, v18, -v227
	v_mul_f32_e32 v227, v7, v21
	v_fma_f32 v246, v6, v20, v227
	v_mul_f32_e32 v227, v6, v21
	v_fma_f32 v247, v7, v20, -v227
	v_add_f32_e32 v22, v0, v244
	v_sub_f32_e32 v24, v0, v244
	v_add_f32_e32 v26, v242, v246
	v_sub_f32_e32 v28, v242, v246
	v_add_f32_e32 v23, v1, v245
	v_sub_f32_e32 v25, v1, v245
	v_add_f32_e32 v27, v243, v247
	v_sub_f32_e32 v29, v243, v247
	v_add_f32_e32 v80, v22, v26
	v_add_f32_e32 v81, v23, v27
	ds_write_b64 v222, v[80:81] offset:32768
	v_sub_f32_e32 v82, v24, v29
	v_add_f32_e32 v83, v25, v28
	ds_write_b64 v222, v[82:83] offset:32800
	v_sub_f32_e32 v84, v22, v26
	v_sub_f32_e32 v85, v23, v27
	ds_write_b64 v222, v[84:85] offset:32832
	v_add_f32_e32 v236, v24, v29
	v_sub_f32_e32 v237, v25, v28
	ds_write_b64 v222, v[236:237] offset:32864
	ds_read_b64 v[0:1], v223 offset:0
	ds_read_b64 v[2:3], v223 offset:32
	ds_read_b64 v[4:5], v223 offset:64
	ds_read_b64 v[6:7], v223 offset:96
	s_waitcnt lgkmcnt(8)
; HD float2 cmul(float2 a, float2 b){ return make_float2(a.x*b.x - a.y*b.y, a.x*b.y + a.y*b.x); }
; HD float2 cmulc(float2 a, float2 b){ return make_float2(a.x*b.x + a.y*b.y, a.y*b.x - a.x*b.y); }
; template<bool INV, bool NOTW>
; HD void bf4c(float2* Z, int i0, int i1, int i2, int i3, float2 w1, float2 w2, float2 w3){
;   float2 a0=Z[i0], a1=Z[i1], a2=Z[i2], a3=Z[i3];
;   if (INV && !NOTW){ a1=cmulc(a1,w1); a2=cmulc(a2,w2); a3=cmulc(a3,w3); }
;   float2 s02=make_float2(a0.x+a2.x,a0.y+a2.y), d02=make_float2(a0.x-a2.x,a0.y-a2.y);
;   float2 s13=make_float2(a1.x+a3.x,a1.y+a3.y), d13=make_float2(a1.x-a3.x,a1.y-a3.y);
;   float2 y0=make_float2(s02.x+s13.x,s02.y+s13.y), y2=make_float2(s02.x-s13.x,s02.y-s13.y);
;   float2 ym=make_float2(d02.x+d13.y,d02.y-d13.x);
;   float2 yp=make_float2(d02.x-d13.y,d02.y+d13.x);
;   float2 y1, y3;
;   if (INV){ y1=yp; y3=ym; } else if (NOTW){ y1=ym; y3=yp; } else { y1=cmul(ym,w1); y2=cmul(y2,w2); y3=cmul(yp,w3); }
;   Z[i0]=y0; Z[i1]=y1; Z[i2]=y2; Z[i3]=y3;
; }
; template<bool INV, int LQ, bool BARRIER=true>
; HD void fft_pass(float2* Z, const float2* twA, const float2* twB, int tid){
;     ...
;   } else {
;     int j=tid&(q-1); int base0=((tid>>LQ)<<(LQ+2))+j;
;     float2 w1=make_float2(1.f,0.f), w2=w1, w3=w1;
;     if (LQ>0){ int k=j*tws; w1=cmul(twA[k>>6],twB[k&63]); w2=cmul(w1,w1); w3=cmul(w2,w1); }
;     _Pragma("unroll") for (int i=0;i<8;++i){ int base=base0+i*2048; bf4c<INV,(LQ==0)>(Z,base,base+q,base+2*q,base+3*q,w1,w2,w3); }
;   }
;   if (BARRIER) __syncthreads(); else asm volatile("s_waitcnt lgkmcnt(0)" ::: "memory");
	v_mul_f32_e32 v227, v11, v17
	v_fma_f32 v242, v10, v16, v227
	v_mul_f32_e32 v227, v10, v17
	v_fma_f32 v243, v11, v16, -v227
	v_mul_f32_e32 v227, v13, v19
	v_fma_f32 v244, v12, v18, v227
	v_mul_f32_e32 v227, v12, v19
	v_fma_f32 v245, v13, v18, -v227
	v_mul_f32_e32 v227, v15, v21
	v_fma_f32 v246, v14, v20, v227
	v_mul_f32_e32 v227, v14, v21
	v_fma_f32 v247, v15, v20, -v227
	v_add_f32_e32 v22, v8, v244
	v_sub_f32_e32 v24, v8, v244
	v_add_f32_e32 v26, v242, v246
	v_sub_f32_e32 v28, v242, v246
	v_add_f32_e32 v23, v9, v245
	v_sub_f32_e32 v25, v9, v245
	v_add_f32_e32 v27, v243, v247
	v_sub_f32_e32 v29, v243, v247
	v_add_f32_e32 v80, v22, v26
	v_add_f32_e32 v81, v23, v27
	ds_write_b64 v222, v[80:81] offset:49152
	v_sub_f32_e32 v82, v24, v29
	v_add_f32_e32 v83, v25, v28
	ds_write_b64 v222, v[82:83] offset:49184
	v_sub_f32_e32 v84, v22, v26
	v_sub_f32_e32 v85, v23, v27
	ds_write_b64 v222, v[84:85] offset:49216
	v_add_f32_e32 v236, v24, v29
	v_sub_f32_e32 v237, v25, v28
	ds_write_b64 v222, v[236:237] offset:49248
	ds_read_b64 v[8:9], v223 offset:16384
	ds_read_b64 v[10:11], v223 offset:16416
	ds_read_b64 v[12:13], v223 offset:16448
	ds_read_b64 v[14:15], v223 offset:16480
	s_waitcnt lgkmcnt(8)
	v_mul_f32_e32 v227, v3, v17
	v_fma_f32 v242, v2, v16, v227
	v_mul_f32_e32 v227, v2, v17
	v_fma_f32 v243, v3, v16, -v227
	v_mul_f32_e32 v227, v5, v19
	v_fma_f32 v244, v4, v18, v227
	v_mul_f32_e32 v227, v4, v19
	v_fma_f32 v245, v5, v18, -v227
	v_mul_f32_e32 v227, v7, v21
	v_fma_f32 v246, v6, v20, v227
	v_mul_f32_e32 v227, v6, v21
	v_fma_f32 v247, v7, v20, -v227
	v_add_f32_e32 v22, v0, v244
	v_sub_f32_e32 v24, v0, v244
	v_add_f32_e32 v26, v242, v246
	v_sub_f32_e32 v28, v242, v246
	v_add_f32_e32 v23, v1, v245
	v_sub_f32_e32 v25, v1, v245
	v_add_f32_e32 v27, v243, v247
	v_sub_f32_e32 v29, v243, v247
	v_add_f32_e32 v80, v22, v26
	v_add_f32_e32 v81, v23, v27
	ds_write_b64 v223, v[80:81] offset:0
	v_sub_f32_e32 v82, v24, v29
	v_add_f32_e32 v83, v25, v28
	ds_write_b64 v223, v[82:83] offset:32
	v_sub_f32_e32 v84, v22, v26
	v_sub_f32_e32 v85, v23, v27
	ds_write_b64 v223, v[84:85] offset:64
	v_add_f32_e32 v236, v24, v29
	v_sub_f32_e32 v237, v25, v28
	ds_write_b64 v223, v[236:237] offset:96
	ds_read_b64 v[0:1], v223 offset:32768
	ds_read_b64 v[2:3], v223 offset:32800
	ds_read_b64 v[4:5], v223 offset:32832
	ds_read_b64 v[6:7], v223 offset:32864
	s_waitcnt lgkmcnt(8)
	v_mul_f32_e32 v227, v11, v17
	v_fma_f32 v242, v10, v16, v227
	v_mul_f32_e32 v227, v10, v17
	v_fma_f32 v243, v11, v16, -v227
	v_mul_f32_e32 v227, v13, v19
	v_fma_f32 v244, v12, v18, v227
	v_mul_f32_e32 v227, v12, v19
	v_fma_f32 v245, v13, v18, -v227
	v_mul_f32_e32 v227, v15, v21
	v_fma_f32 v246, v14, v20, v227
	v_mul_f32_e32 v227, v14, v21
	v_fma_f32 v247, v15, v20, -v227
	v_add_f32_e32 v22, v8, v244
	v_sub_f32_e32 v24, v8, v244
	v_add_f32_e32 v26, v242, v246
	v_sub_f32_e32 v28, v242, v246
	v_add_f32_e32 v23, v9, v245
	v_sub_f32_e32 v25, v9, v245
	v_add_f32_e32 v27, v243, v247
	v_sub_f32_e32 v29, v243, v247
	v_add_f32_e32 v80, v22, v26
	v_add_f32_e32 v81, v23, v27
	ds_write_b64 v223, v[80:81] offset:16384
	v_sub_f32_e32 v82, v24, v29
	v_add_f32_e32 v83, v25, v28
	ds_write_b64 v223, v[82:83] offset:16416
	v_sub_f32_e32 v84, v22, v26
	v_sub_f32_e32 v85, v23, v27
	ds_write_b64 v223, v[84:85] offset:16448
	v_add_f32_e32 v236, v24, v29
	v_sub_f32_e32 v237, v25, v28
	ds_write_b64 v223, v[236:237] offset:16480
	ds_read_b64 v[8:9], v223 offset:49152
	ds_read_b64 v[10:11], v223 offset:49184
	ds_read_b64 v[12:13], v223 offset:49216
	ds_read_b64 v[14:15], v223 offset:49248
	s_waitcnt lgkmcnt(8)
	v_mul_f32_e32 v227, v3, v17
	v_fma_f32 v242, v2, v16, v227
	v_mul_f32_e32 v227, v2, v17
	v_fma_f32 v243, v3, v16, -v227
	v_mul_f32_e32 v227, v5, v19
	v_fma_f32 v244, v4, v18, v227
	v_mul_f32_e32 v227, v4, v19
	v_fma_f32 v245, v5, v18, -v227
	v_mul_f32_e32 v227, v7, v21
	v_fma_f32 v246, v6, v20, v227
	v_mul_f32_e32 v227, v6, v21
	v_fma_f32 v247, v7, v20, -v227
	v_add_f32_e32 v22, v0, v244
	v_sub_f32_e32 v24, v0, v244
	v_add_f32_e32 v26, v242, v246
	v_sub_f32_e32 v28, v242, v246
	v_add_f32_e32 v23, v1, v245
	v_sub_f32_e32 v25, v1, v245
	v_add_f32_e32 v27, v243, v247
	v_sub_f32_e32 v29, v243, v247
	v_add_f32_e32 v80, v22, v26
	v_add_f32_e32 v81, v23, v27
	ds_write_b64 v223, v[80:81] offset:32768
	v_sub_f32_e32 v82, v24, v29
	v_add_f32_e32 v83, v25, v28
	ds_write_b64 v223, v[82:83] offset:32800
	v_sub_f32_e32 v84, v22, v26
	v_sub_f32_e32 v85, v23, v27
	ds_write_b64 v223, v[84:85] offset:32832
	v_add_f32_e32 v236, v24, v29
	v_sub_f32_e32 v237, v25, v28
	ds_write_b64 v223, v[236:237] offset:32864
	s_waitcnt lgkmcnt(4)
	v_mul_f32_e32 v227, v11, v17
	v_fma_f32 v242, v10, v16, v227
	v_mul_f32_e32 v227, v10, v17
	v_fma_f32 v243, v11, v16, -v227
	v_mul_f32_e32 v227, v13, v19
	v_fma_f32 v244, v12, v18, v227
	v_mul_f32_e32 v227, v12, v19
	v_fma_f32 v245, v13, v18, -v227
	v_mul_f32_e32 v227, v15, v21
	v_fma_f32 v246, v14, v20, v227
	v_mul_f32_e32 v227, v14, v21
	v_fma_f32 v247, v15, v20, -v227
	v_add_f32_e32 v22, v8, v244
	v_sub_f32_e32 v24, v8, v244
	v_add_f32_e32 v26, v242, v246
	v_sub_f32_e32 v28, v242, v246
	v_add_f32_e32 v23, v9, v245
	v_sub_f32_e32 v25, v9, v245
	v_add_f32_e32 v27, v243, v247
	v_sub_f32_e32 v29, v243, v247
	v_add_f32_e32 v80, v22, v26
	v_add_f32_e32 v81, v23, v27
	ds_write_b64 v223, v[80:81] offset:49152
	v_sub_f32_e32 v82, v24, v29
	v_add_f32_e32 v83, v25, v28
	ds_write_b64 v223, v[82:83] offset:49184
	v_sub_f32_e32 v84, v22, v26
	v_sub_f32_e32 v85, v23, v27
	ds_write_b64 v223, v[84:85] offset:49216
	v_add_f32_e32 v236, v24, v29
	v_sub_f32_e32 v237, v25, v28
	ds_write_b64 v223, v[236:237] offset:49248
	s_waitcnt lgkmcnt(0)
; HD float2 cmul(float2 a, float2 b){ return make_float2(a.x*b.x - a.y*b.y, a.x*b.y + a.y*b.x); }
; HD float2 cmulc(float2 a, float2 b){ return make_float2(a.x*b.x + a.y*b.y, a.y*b.x - a.x*b.y); }
; template<bool INV, bool NOTW>
; HD void bf4c(float2* Z, int i0, int i1, int i2, int i3, float2 w1, float2 w2, float2 w3){
;   float2 a0=Z[i0], a1=Z[i1], a2=Z[i2], a3=Z[i3];
;   if (INV && !NOTW){ a1=cmulc(a1,w1); a2=cmulc(a2,w2); a3=cmulc(a3,w3); }
;   float2 s02=make_float2(a0.x+a2.x,a0.y+a2.y), d02=make_float2(a0.x-a2.x,a0.y-a2.y);
;   float2 s13=make_float2(a1.x+a3.x,a1.y+a3.y), d13=make_float2(a1.x-a3.x,a1.y-a3.y);
;   float2 y0=make_float2(s02.x+s13.x,s02.y+s13.y), y2=make_float2(s02.x-s13.x,s02.y-s13.y);
;   float2 ym=make_float2(d02.x+d13.y,d02.y-d13.x);
;   float2 yp=make_float2(d02.x-d13.y,d02.y+d13.x);
;   float2 y1, y3;
;   if (INV){ y1=yp; y3=ym; } else if (NOTW){ y1=ym; y3=yp; } else { y1=cmul(ym,w1); y2=cmul(y2,w2); y3=cmul(yp,w3); }
;   Z[i0]=y0; Z[i1]=y1; Z[i2]=y2; Z[i3]=y3;
; }
; template<bool INV, int LQ, bool BARRIER=true>
; HD void fft_pass(float2* Z, const float2* twA, const float2* twB, int tid){
;     ...
;   } else {
;     int j=tid&(q-1); int base0=((tid>>LQ)<<(LQ+2))+j;
;     float2 w1=make_float2(1.f,0.f), w2=w1, w3=w1;
;     if (LQ>0){ int k=j*tws; w1=cmul(twA[k>>6],twB[k&63]); w2=cmul(w1,w1); w3=cmul(w2,w1); }
;     _Pragma("unroll") for (int i=0;i<8;++i){ int base=base0+i*2048; bf4c<INV,(LQ==0)>(Z,base,base+q,base+2*q,base+3*q,w1,w2,w3); }
;   }
;   if (BARRIER) __syncthreads(); else asm volatile("s_waitcnt lgkmcnt(0)" ::: "memory");
	v_and_b32_e32 v226, 15, v154
	v_lshlrev_b32_e32 v224, 5, v226
	v_add_u32_e32 v224, 0x20800, v224
	v_mov_b32_e32 v225, 0x20a00
	ds_read_b64 v[238:239], v224
	ds_read_b64 v[240:241], v225
	s_waitcnt lgkmcnt(0)
	v_mul_f32_e32 v227, v239, v241
	v_fma_f32 v16, v238, v240, -v227
	v_mul_f32_e32 v227, v239, v240
	v_fma_f32 v17, v238, v241, v227
	v_mul_f32_e32 v227, v17, v17
	v_fma_f32 v18, v16, v16, -v227
	v_mul_f32_e32 v227, v17, v16
	v_fma_f32 v19, v16, v17, v227
	v_mul_f32_e32 v227, v19, v17
	v_fma_f32 v20, v18, v16, -v227
	v_mul_f32_e32 v227, v19, v16
	v_fma_f32 v21, v18, v17, v227
	v_lshrrev_b32_e32 v222, 4, v154
	v_lshlrev_b32_e32 v222, 6, v222
	v_add_u32_e32 v222, v222, v226
	v_lshlrev_b32_e32 v222, 3, v222
	v_add_u32_e32 v223, 0x10000, v222
	ds_read_b64 v[0:1], v222 offset:0
	ds_read_b64 v[2:3], v222 offset:128
	ds_read_b64 v[4:5], v222 offset:256
	ds_read_b64 v[6:7], v222 offset:384
	ds_read_b64 v[8:9], v222 offset:16384
	ds_read_b64 v[10:11], v222 offset:16512
	ds_read_b64 v[12:13], v222 offset:16640
	ds_read_b64 v[14:15], v222 offset:16768
	s_waitcnt lgkmcnt(4)
	v_mul_f32_e32 v227, v3, v17
	v_fma_f32 v242, v2, v16, v227
	v_mul_f32_e32 v227, v2, v17
	v_fma_f32 v243, v3, v16, -v227
	v_mul_f32_e32 v227, v5, v19
	v_fma_f32 v244, v4, v18, v227
	v_mul_f32_e32 v227, v4, v19
	v_fma_f32 v245, v5, v18, -v227
	v_mul_f32_e32 v227, v7, v21
	v_fma_f32 v246, v6, v20, v227
	v_mul_f32_e32 v227, v6, v21
	v_fma_f32 v247, v7, v20, -v227
	v_add_f32_e32 v22, v0, v244
	v_sub_f32_e32 v24, v0, v244
	v_add_f32_e32 v26, v242, v246
	v_sub_f32_e32 v28, v242, v246
	v_add_f32_e32 v23, v1, v245
	v_sub_f32_e32 v25, v1, v245
	v_add_f32_e32 v27, v243, v247
	v_sub_f32_e32 v29, v243, v247
	v_add_f32_e32 v80, v22, v26
	v_add_f32_e32 v81, v23, v27
	ds_write_b64 v222, v[80:81] offset:0
	v_sub_f32_e32 v82, v24, v29
	v_add_f32_e32 v83, v25, v28
	ds_write_b64 v222, v[82:83] offset:128
	v_sub_f32_e32 v84, v22, v26
	v_sub_f32_e32 v85, v23, v27
	ds_write_b64 v222, v[84:85] offset:256
	v_add_f32_e32 v236, v24, v29
	v_sub_f32_e32 v237, v25, v28
	ds_write_b64 v222, v[236:237] offset:384
	ds_read_b64 v[0:1], v222 offset:32768
	ds_read_b64 v[2:3], v222 offset:32896
	ds_read_b64 v[4:5], v222 offset:33024
	ds_read_b64 v[6:7], v222 offset:33152
	s_waitcnt lgkmcnt(8)
	v_mul_f32_e32 v227, v11, v17
	v_fma_f32 v242, v10, v16, v227
	v_mul_f32_e32 v227, v10, v17
	v_fma_f32 v243, v11, v16, -v227
	v_mul_f32_e32 v227, v13, v19
	v_fma_f32 v244, v12, v18, v227
	v_mul_f32_e32 v227, v12, v19
	v_fma_f32 v245, v13, v18, -v227
	v_mul_f32_e32 v227, v15, v21
	v_fma_f32 v246, v14, v20, v227
	v_mul_f32_e32 v227, v14, v21
	v_fma_f32 v247, v15, v20, -v227
	v_add_f32_e32 v22, v8, v244
	v_sub_f32_e32 v24, v8, v244
	v_add_f32_e32 v26, v242, v246
	v_sub_f32_e32 v28, v242, v246
	v_add_f32_e32 v23, v9, v245
	v_sub_f32_e32 v25, v9, v245
	v_add_f32_e32 v27, v243, v247
	v_sub_f32_e32 v29, v243, v247
	v_add_f32_e32 v80, v22, v26
	v_add_f32_e32 v81, v23, v27
	ds_write_b64 v222, v[80:81] offset:16384
	v_sub_f32_e32 v82, v24, v29
	v_add_f32_e32 v83, v25, v28
	ds_write_b64 v222, v[82:83] offset:16512
	v_sub_f32_e32 v84, v22, v26
	v_sub_f32_e32 v85, v23, v27
	ds_write_b64 v222, v[84:85] offset:16640
	v_add_f32_e32 v236, v24, v29
	v_sub_f32_e32 v237, v25, v28
	ds_write_b64 v222, v[236:237] offset:16768
	ds_read_b64 v[8:9], v222 offset:49152
	ds_read_b64 v[10:11], v222 offset:49280
	ds_read_b64 v[12:13], v222 offset:49408
	ds_read_b64 v[14:15], v222 offset:49536
	s_waitcnt lgkmcnt(8)
	v_mul_f32_e32 v227, v3, v17
	v_fma_f32 v242, v2, v16, v227
	v_mul_f32_e32 v227, v2, v17
	v_fma_f32 v243, v3, v16, -v227
	v_mul_f32_e32 v227, v5, v19
	v_fma_f32 v244, v4, v18, v227
	v_mul_f32_e32 v227, v4, v19
	v_fma_f32 v245, v5, v18, -v227
	v_mul_f32_e32 v227, v7, v21
	v_fma_f32 v246, v6, v20, v227
	v_mul_f32_e32 v227, v6, v21
	v_fma_f32 v247, v7, v20, -v227
	v_add_f32_e32 v22, v0, v244
	v_sub_f32_e32 v24, v0, v244
	v_add_f32_e32 v26, v242, v246
	v_sub_f32_e32 v28, v242, v246
	v_add_f32_e32 v23, v1, v245
	v_sub_f32_e32 v25, v1, v245
	v_add_f32_e32 v27, v243, v247
	v_sub_f32_e32 v29, v243, v247
	v_add_f32_e32 v80, v22, v26
	v_add_f32_e32 v81, v23, v27
	ds_write_b64 v222, v[80:81] offset:32768
	v_sub_f32_e32 v82, v24, v29
	v_add_f32_e32 v83, v25, v28
	ds_write_b64 v222, v[82:83] offset:32896
	v_sub_f32_e32 v84, v22, v26
	v_sub_f32_e32 v85, v23, v27
	ds_write_b64 v222, v[84:85] offset:33024
	v_add_f32_e32 v236, v24, v29
	v_sub_f32_e32 v237, v25, v28
	ds_write_b64 v222, v[236:237] offset:33152
	ds_read_b64 v[0:1], v223 offset:0
	ds_read_b64 v[2:3], v223 offset:128
	ds_read_b64 v[4:5], v223 offset:256
	ds_read_b64 v[6:7], v223 offset:384
	s_waitcnt lgkmcnt(8)
	v_mul_f32_e32 v227, v11, v17
	v_fma_f32 v242, v10, v16, v227
	v_mul_f32_e32 v227, v10, v17
	v_fma_f32 v243, v11, v16, -v227
	v_mul_f32_e32 v227, v13, v19
	v_fma_f32 v244, v12, v18, v227
	v_mul_f32_e32 v227, v12, v19
	v_fma_f32 v245, v13, v18, -v227
	v_mul_f32_e32 v227, v15, v21
	v_fma_f32 v246, v14, v20, v227
	v_mul_f32_e32 v227, v14, v21
	v_fma_f32 v247, v15, v20, -v227
	v_add_f32_e32 v22, v8, v244
	v_sub_f32_e32 v24, v8, v244
	v_add_f32_e32 v26, v242, v246
	v_sub_f32_e32 v28, v242, v246
	v_add_f32_e32 v23, v9, v245
	v_sub_f32_e32 v25, v9, v245
	v_add_f32_e32 v27, v243, v247
	v_sub_f32_e32 v29, v243, v247
	v_add_f32_e32 v80, v22, v26
	v_add_f32_e32 v81, v23, v27
	ds_write_b64 v222, v[80:81] offset:49152
	v_sub_f32_e32 v82, v24, v29
	v_add_f32_e32 v83, v25, v28
	ds_write_b64 v222, v[82:83] offset:49280
	v_sub_f32_e32 v84, v22, v26
	v_sub_f32_e32 v85, v23, v27
	ds_write_b64 v222, v[84:85] offset:49408
	v_add_f32_e32 v236, v24, v29
	v_sub_f32_e32 v237, v25, v28
	ds_write_b64 v222, v[236:237] offset:49536
	ds_read_b64 v[8:9], v223 offset:16384
	ds_read_b64 v[10:11], v223 offset:16512
	ds_read_b64 v[12:13], v223 offset:16640
	ds_read_b64 v[14:15], v223 offset:16768
	s_waitcnt lgkmcnt(8)
; HD float2 cmul(float2 a, float2 b){ return make_float2(a.x*b.x - a.y*b.y, a.x*b.y + a.y*b.x); }
; HD float2 cmulc(float2 a, float2 b){ return make_float2(a.x*b.x + a.y*b.y, a.y*b.x - a.x*b.y); }
; template<bool INV, bool NOTW>
; HD void bf4c(float2* Z, int i0, int i1, int i2, int i3, float2 w1, float2 w2, float2 w3){
;   float2 a0=Z[i0], a1=Z[i1], a2=Z[i2], a3=Z[i3];
;   if (INV && !NOTW){ a1=cmulc(a1,w1); a2=cmulc(a2,w2); a3=cmulc(a3,w3); }
;   float2 s02=make_float2(a0.x+a2.x,a0.y+a2.y), d02=make_float2(a0.x-a2.x,a0.y-a2.y);
;   float2 s13=make_float2(a1.x+a3.x,a1.y+a3.y), d13=make_float2(a1.x-a3.x,a1.y-a3.y);
;   float2 y0=make_float2(s02.x+s13.x,s02.y+s13.y), y2=make_float2(s02.x-s13.x,s02.y-s13.y);
;   float2 ym=make_float2(d02.x+d13.y,d02.y-d13.x);
;   float2 yp=make_float2(d02.x-d13.y,d02.y+d13.x);
;   float2 y1, y3;
;   if (INV){ y1=yp; y3=ym; } else if (NOTW){ y1=ym; y3=yp; } else { y1=cmul(ym,w1); y2=cmul(y2,w2); y3=cmul(yp,w3); }
;   Z[i0]=y0; Z[i1]=y1; Z[i2]=y2; Z[i3]=y3;
; }
; template<bool INV, int LQ, bool BARRIER=true>
; HD void fft_pass(float2* Z, const float2* twA, const float2* twB, int tid){
;     ...
;   } else {
;     int j=tid&(q-1); int base0=((tid>>LQ)<<(LQ+2))+j;
;     float2 w1=make_float2(1.f,0.f), w2=w1, w3=w1;
;     if (LQ>0){ int k=j*tws; w1=cmul(twA[k>>6],twB[k&63]); w2=cmul(w1,w1); w3=cmul(w2,w1); }
;     _Pragma("unroll") for (int i=0;i<8;++i){ int base=base0+i*2048; bf4c<INV,(LQ==0)>(Z,base,base+q,base+2*q,base+3*q,w1,w2,w3); }
;   }
;   if (BARRIER) __syncthreads(); else asm volatile("s_waitcnt lgkmcnt(0)" ::: "memory");
	v_mul_f32_e32 v227, v3, v17
	v_fma_f32 v242, v2, v16, v227
	v_mul_f32_e32 v227, v2, v17
	v_fma_f32 v243, v3, v16, -v227
	v_mul_f32_e32 v227, v5, v19
	v_fma_f32 v244, v4, v18, v227
	v_mul_f32_e32 v227, v4, v19
	v_fma_f32 v245, v5, v18, -v227
	v_mul_f32_e32 v227, v7, v21
	v_fma_f32 v246, v6, v20, v227
	v_mul_f32_e32 v227, v6, v21
	v_fma_f32 v247, v7, v20, -v227
	v_add_f32_e32 v22, v0, v244
	v_sub_f32_e32 v24, v0, v244
	v_add_f32_e32 v26, v242, v246
	v_sub_f32_e32 v28, v242, v246
	v_add_f32_e32 v23, v1, v245
	v_sub_f32_e32 v25, v1, v245
	v_add_f32_e32 v27, v243, v247
	v_sub_f32_e32 v29, v243, v247
	v_add_f32_e32 v80, v22, v26
	v_add_f32_e32 v81, v23, v27
	ds_write_b64 v223, v[80:81] offset:0
	v_sub_f32_e32 v82, v24, v29
	v_add_f32_e32 v83, v25, v28
	ds_write_b64 v223, v[82:83] offset:128
	v_sub_f32_e32 v84, v22, v26
	v_sub_f32_e32 v85, v23, v27
	ds_write_b64 v223, v[84:85] offset:256
	v_add_f32_e32 v236, v24, v29
	v_sub_f32_e32 v237, v25, v28
	ds_write_b64 v223, v[236:237] offset:384
	ds_read_b64 v[0:1], v223 offset:32768
	ds_read_b64 v[2:3], v223 offset:32896
	ds_read_b64 v[4:5], v223 offset:33024
	ds_read_b64 v[6:7], v223 offset:33152
	s_waitcnt lgkmcnt(8)
	v_mul_f32_e32 v227, v11, v17
	v_fma_f32 v242, v10, v16, v227
	v_mul_f32_e32 v227, v10, v17
	v_fma_f32 v243, v11, v16, -v227
	v_mul_f32_e32 v227, v13, v19
	v_fma_f32 v244, v12, v18, v227
	v_mul_f32_e32 v227, v12, v19
	v_fma_f32 v245, v13, v18, -v227
	v_mul_f32_e32 v227, v15, v21
	v_fma_f32 v246, v14, v20, v227
	v_mul_f32_e32 v227, v14, v21
	v_fma_f32 v247, v15, v20, -v227
	v_add_f32_e32 v22, v8, v244
	v_sub_f32_e32 v24, v8, v244
	v_add_f32_e32 v26, v242, v246
	v_sub_f32_e32 v28, v242, v246
	v_add_f32_e32 v23, v9, v245
	v_sub_f32_e32 v25, v9, v245
	v_add_f32_e32 v27, v243, v247
	v_sub_f32_e32 v29, v243, v247
	v_add_f32_e32 v80, v22, v26
	v_add_f32_e32 v81, v23, v27
	ds_write_b64 v223, v[80:81] offset:16384
	v_sub_f32_e32 v82, v24, v29
	v_add_f32_e32 v83, v25, v28
	ds_write_b64 v223, v[82:83] offset:16512
	v_sub_f32_e32 v84, v22, v26
	v_sub_f32_e32 v85, v23, v27
	ds_write_b64 v223, v[84:85] offset:16640
	v_add_f32_e32 v236, v24, v29
	v_sub_f32_e32 v237, v25, v28
	ds_write_b64 v223, v[236:237] offset:16768
	ds_read_b64 v[8:9], v223 offset:49152
	ds_read_b64 v[10:11], v223 offset:49280
	ds_read_b64 v[12:13], v223 offset:49408
	ds_read_b64 v[14:15], v223 offset:49536
	s_waitcnt lgkmcnt(8)
	v_mul_f32_e32 v227, v3, v17
	v_fma_f32 v242, v2, v16, v227
	v_mul_f32_e32 v227, v2, v17
	v_fma_f32 v243, v3, v16, -v227
	v_mul_f32_e32 v227, v5, v19
	v_fma_f32 v244, v4, v18, v227
	v_mul_f32_e32 v227, v4, v19
	v_fma_f32 v245, v5, v18, -v227
	v_mul_f32_e32 v227, v7, v21
	v_fma_f32 v246, v6, v20, v227
	v_mul_f32_e32 v227, v6, v21
	v_fma_f32 v247, v7, v20, -v227
	v_add_f32_e32 v22, v0, v244
	v_sub_f32_e32 v24, v0, v244
	v_add_f32_e32 v26, v242, v246
	v_sub_f32_e32 v28, v242, v246
	v_add_f32_e32 v23, v1, v245
	v_sub_f32_e32 v25, v1, v245
	v_add_f32_e32 v27, v243, v247
	v_sub_f32_e32 v29, v243, v247
	v_add_f32_e32 v80, v22, v26
	v_add_f32_e32 v81, v23, v27
	ds_write_b64 v223, v[80:81] offset:32768
	v_sub_f32_e32 v82, v24, v29
	v_add_f32_e32 v83, v25, v28
	ds_write_b64 v223, v[82:83] offset:32896
	v_sub_f32_e32 v84, v22, v26
	v_sub_f32_e32 v85, v23, v27
	ds_write_b64 v223, v[84:85] offset:33024
	v_add_f32_e32 v236, v24, v29
	v_sub_f32_e32 v237, v25, v28
	ds_write_b64 v223, v[236:237] offset:33152
	s_waitcnt lgkmcnt(4)
	v_mul_f32_e32 v227, v11, v17
	v_fma_f32 v242, v10, v16, v227
	v_mul_f32_e32 v227, v10, v17
	v_fma_f32 v243, v11, v16, -v227
	v_mul_f32_e32 v227, v13, v19
	v_fma_f32 v244, v12, v18, v227
	v_mul_f32_e32 v227, v12, v19
	v_fma_f32 v245, v13, v18, -v227
	v_mul_f32_e32 v227, v15, v21
	v_fma_f32 v246, v14, v20, v227
	v_mul_f32_e32 v227, v14, v21
	v_fma_f32 v247, v15, v20, -v227
	v_add_f32_e32 v22, v8, v244
	v_sub_f32_e32 v24, v8, v244
	v_add_f32_e32 v26, v242, v246
	v_sub_f32_e32 v28, v242, v246
	v_add_f32_e32 v23, v9, v245
	v_sub_f32_e32 v25, v9, v245
	v_add_f32_e32 v27, v243, v247
	v_sub_f32_e32 v29, v243, v247
	v_add_f32_e32 v80, v22, v26
	v_add_f32_e32 v81, v23, v27
	ds_write_b64 v223, v[80:81] offset:49152
	v_sub_f32_e32 v82, v24, v29
	v_add_f32_e32 v83, v25, v28
	ds_write_b64 v223, v[82:83] offset:49280
	v_sub_f32_e32 v84, v22, v26
	v_sub_f32_e32 v85, v23, v27
	ds_write_b64 v223, v[84:85] offset:49408
	v_add_f32_e32 v236, v24, v29
	v_sub_f32_e32 v237, v25, v28
	ds_write_b64 v223, v[236:237] offset:49536
	s_waitcnt lgkmcnt(0)
	v_and_b32_e32 v226, 63, v154
	v_lshlrev_b32_e32 v224, 3, v226
	v_add_u32_e32 v224, 0x20800, v224
	v_mov_b32_e32 v225, 0x20a00
	ds_read_b64 v[238:239], v224
	ds_read_b64 v[240:241], v225
	s_waitcnt lgkmcnt(0)
	v_mul_f32_e32 v227, v239, v241
	v_fma_f32 v16, v238, v240, -v227
	v_mul_f32_e32 v227, v239, v240
	v_fma_f32 v17, v238, v241, v227
	v_mul_f32_e32 v227, v17, v17
	v_fma_f32 v18, v16, v16, -v227
	v_mul_f32_e32 v227, v17, v16
	v_fma_f32 v19, v16, v17, v227
	v_mul_f32_e32 v227, v19, v17
	v_fma_f32 v20, v18, v16, -v227
	v_mul_f32_e32 v227, v19, v16
	v_fma_f32 v21, v18, v17, v227
	v_lshrrev_b32_e32 v222, 6, v154
	v_lshlrev_b32_e32 v222, 8, v222
	v_add_u32_e32 v222, v222, v226
	v_lshlrev_b32_e32 v222, 3, v222
	v_add_u32_e32 v223, 0x10000, v222
	ds_read_b64 v[0:1], v222 offset:0
	ds_read_b64 v[2:3], v222 offset:512
	ds_read_b64 v[4:5], v222 offset:1024
	ds_read_b64 v[6:7], v222 offset:1536
	ds_read_b64 v[8:9], v222 offset:16384
	ds_read_b64 v[10:11], v222 offset:16896
	ds_read_b64 v[12:13], v222 offset:17408
	ds_read_b64 v[14:15], v222 offset:17920
	s_waitcnt lgkmcnt(4)
; HD float2 cmul(float2 a, float2 b){ return make_float2(a.x*b.x - a.y*b.y, a.x*b.y + a.y*b.x); }
; HD float2 cmulc(float2 a, float2 b){ return make_float2(a.x*b.x + a.y*b.y, a.y*b.x - a.x*b.y); }
; template<bool INV, bool NOTW>
; HD void bf4c(float2* Z, int i0, int i1, int i2, int i3, float2 w1, float2 w2, float2 w3){
;   float2 a0=Z[i0], a1=Z[i1], a2=Z[i2], a3=Z[i3];
;   if (INV && !NOTW){ a1=cmulc(a1,w1); a2=cmulc(a2,w2); a3=cmulc(a3,w3); }
;   float2 s02=make_float2(a0.x+a2.x,a0.y+a2.y), d02=make_float2(a0.x-a2.x,a0.y-a2.y);
;   float2 s13=make_float2(a1.x+a3.x,a1.y+a3.y), d13=make_float2(a1.x-a3.x,a1.y-a3.y);
;   float2 y0=make_float2(s02.x+s13.x,s02.y+s13.y), y2=make_float2(s02.x-s13.x,s02.y-s13.y);
;   float2 ym=make_float2(d02.x+d13.y,d02.y-d13.x);
;   float2 yp=make_float2(d02.x-d13.y,d02.y+d13.x);
;   float2 y1, y3;
;   if (INV){ y1=yp; y3=ym; } else if (NOTW){ y1=ym; y3=yp; } else { y1=cmul(ym,w1); y2=cmul(y2,w2); y3=cmul(yp,w3); }
;   Z[i0]=y0; Z[i1]=y1; Z[i2]=y2; Z[i3]=y3;
; }
; template<bool INV, int LQ, bool BARRIER=true>
; HD void fft_pass(float2* Z, const float2* twA, const float2* twB, int tid){
;     ...
;   } else {
;     int j=tid&(q-1); int base0=((tid>>LQ)<<(LQ+2))+j;
;     float2 w1=make_float2(1.f,0.f), w2=w1, w3=w1;
;     if (LQ>0){ int k=j*tws; w1=cmul(twA[k>>6],twB[k&63]); w2=cmul(w1,w1); w3=cmul(w2,w1); }
;     _Pragma("unroll") for (int i=0;i<8;++i){ int base=base0+i*2048; bf4c<INV,(LQ==0)>(Z,base,base+q,base+2*q,base+3*q,w1,w2,w3); }
;   }
;   if (BARRIER) __syncthreads(); else asm volatile("s_waitcnt lgkmcnt(0)" ::: "memory");
	v_mul_f32_e32 v227, v3, v17
	v_fma_f32 v242, v2, v16, v227
	v_mul_f32_e32 v227, v2, v17
	v_fma_f32 v243, v3, v16, -v227
	v_mul_f32_e32 v227, v5, v19
	v_fma_f32 v244, v4, v18, v227
	v_mul_f32_e32 v227, v4, v19
	v_fma_f32 v245, v5, v18, -v227
	v_mul_f32_e32 v227, v7, v21
	v_fma_f32 v246, v6, v20, v227
	v_mul_f32_e32 v227, v6, v21
	v_fma_f32 v247, v7, v20, -v227
	v_add_f32_e32 v22, v0, v244
	v_sub_f32_e32 v24, v0, v244
	v_add_f32_e32 v26, v242, v246
	v_sub_f32_e32 v28, v242, v246
	v_add_f32_e32 v23, v1, v245
	v_sub_f32_e32 v25, v1, v245
	v_add_f32_e32 v27, v243, v247
	v_sub_f32_e32 v29, v243, v247
	v_add_f32_e32 v80, v22, v26
	v_add_f32_e32 v81, v23, v27
	ds_write_b64 v222, v[80:81] offset:0
	v_sub_f32_e32 v82, v24, v29
	v_add_f32_e32 v83, v25, v28
	ds_write_b64 v222, v[82:83] offset:512
	v_sub_f32_e32 v84, v22, v26
	v_sub_f32_e32 v85, v23, v27
	ds_write_b64 v222, v[84:85] offset:1024
	v_add_f32_e32 v236, v24, v29
	v_sub_f32_e32 v237, v25, v28
	ds_write_b64 v222, v[236:237] offset:1536
	ds_read_b64 v[0:1], v222 offset:32768
	ds_read_b64 v[2:3], v222 offset:33280
	ds_read_b64 v[4:5], v222 offset:33792
	ds_read_b64 v[6:7], v222 offset:34304
	s_waitcnt lgkmcnt(8)
	v_mul_f32_e32 v227, v11, v17
	v_fma_f32 v242, v10, v16, v227
	v_mul_f32_e32 v227, v10, v17
	v_fma_f32 v243, v11, v16, -v227
	v_mul_f32_e32 v227, v13, v19
	v_fma_f32 v244, v12, v18, v227
	v_mul_f32_e32 v227, v12, v19
	v_fma_f32 v245, v13, v18, -v227
	v_mul_f32_e32 v227, v15, v21
	v_fma_f32 v246, v14, v20, v227
	v_mul_f32_e32 v227, v14, v21
	v_fma_f32 v247, v15, v20, -v227
	v_add_f32_e32 v22, v8, v244
	v_sub_f32_e32 v24, v8, v244
	v_add_f32_e32 v26, v242, v246
	v_sub_f32_e32 v28, v242, v246
	v_add_f32_e32 v23, v9, v245
	v_sub_f32_e32 v25, v9, v245
	v_add_f32_e32 v27, v243, v247
	v_sub_f32_e32 v29, v243, v247
	v_add_f32_e32 v80, v22, v26
	v_add_f32_e32 v81, v23, v27
	ds_write_b64 v222, v[80:81] offset:16384
	v_sub_f32_e32 v82, v24, v29
	v_add_f32_e32 v83, v25, v28
	ds_write_b64 v222, v[82:83] offset:16896
	v_sub_f32_e32 v84, v22, v26
	v_sub_f32_e32 v85, v23, v27
	ds_write_b64 v222, v[84:85] offset:17408
	v_add_f32_e32 v236, v24, v29
	v_sub_f32_e32 v237, v25, v28
	ds_write_b64 v222, v[236:237] offset:17920
	ds_read_b64 v[8:9], v222 offset:49152
	ds_read_b64 v[10:11], v222 offset:49664
	ds_read_b64 v[12:13], v222 offset:50176
	ds_read_b64 v[14:15], v222 offset:50688
	s_waitcnt lgkmcnt(8)
	v_mul_f32_e32 v227, v3, v17
	v_fma_f32 v242, v2, v16, v227
	v_mul_f32_e32 v227, v2, v17
	v_fma_f32 v243, v3, v16, -v227
	v_mul_f32_e32 v227, v5, v19
	v_fma_f32 v244, v4, v18, v227
	v_mul_f32_e32 v227, v4, v19
	v_fma_f32 v245, v5, v18, -v227
	v_mul_f32_e32 v227, v7, v21
	v_fma_f32 v246, v6, v20, v227
	v_mul_f32_e32 v227, v6, v21
	v_fma_f32 v247, v7, v20, -v227
	v_add_f32_e32 v22, v0, v244
	v_sub_f32_e32 v24, v0, v244
	v_add_f32_e32 v26, v242, v246
	v_sub_f32_e32 v28, v242, v246
	v_add_f32_e32 v23, v1, v245
	v_sub_f32_e32 v25, v1, v245
	v_add_f32_e32 v27, v243, v247
	v_sub_f32_e32 v29, v243, v247
	v_add_f32_e32 v80, v22, v26
	v_add_f32_e32 v81, v23, v27
	ds_write_b64 v222, v[80:81] offset:32768
	v_sub_f32_e32 v82, v24, v29
	v_add_f32_e32 v83, v25, v28
	ds_write_b64 v222, v[82:83] offset:33280
	v_sub_f32_e32 v84, v22, v26
	v_sub_f32_e32 v85, v23, v27
	ds_write_b64 v222, v[84:85] offset:33792
	v_add_f32_e32 v236, v24, v29
	v_sub_f32_e32 v237, v25, v28
	ds_write_b64 v222, v[236:237] offset:34304
	ds_read_b64 v[0:1], v223 offset:0
	ds_read_b64 v[2:3], v223 offset:512
	ds_read_b64 v[4:5], v223 offset:1024
	ds_read_b64 v[6:7], v223 offset:1536
	s_waitcnt lgkmcnt(8)
	v_mul_f32_e32 v227, v11, v17
	v_fma_f32 v242, v10, v16, v227
	v_mul_f32_e32 v227, v10, v17
	v_fma_f32 v243, v11, v16, -v227
	v_mul_f32_e32 v227, v13, v19
	v_fma_f32 v244, v12, v18, v227
	v_mul_f32_e32 v227, v12, v19
	v_fma_f32 v245, v13, v18, -v227
	v_mul_f32_e32 v227, v15, v21
	v_fma_f32 v246, v14, v20, v227
	v_mul_f32_e32 v227, v14, v21
	v_fma_f32 v247, v15, v20, -v227
	v_add_f32_e32 v22, v8, v244
	v_sub_f32_e32 v24, v8, v244
	v_add_f32_e32 v26, v242, v246
	v_sub_f32_e32 v28, v242, v246
	v_add_f32_e32 v23, v9, v245
	v_sub_f32_e32 v25, v9, v245
	v_add_f32_e32 v27, v243, v247
	v_sub_f32_e32 v29, v243, v247
	v_add_f32_e32 v80, v22, v26
	v_add_f32_e32 v81, v23, v27
	ds_write_b64 v222, v[80:81] offset:49152
	v_sub_f32_e32 v82, v24, v29
	v_add_f32_e32 v83, v25, v28
	ds_write_b64 v222, v[82:83] offset:49664
	v_sub_f32_e32 v84, v22, v26
	v_sub_f32_e32 v85, v23, v27
	ds_write_b64 v222, v[84:85] offset:50176
	v_add_f32_e32 v236, v24, v29
	v_sub_f32_e32 v237, v25, v28
	ds_write_b64 v222, v[236:237] offset:50688
	ds_read_b64 v[8:9], v223 offset:16384
	ds_read_b64 v[10:11], v223 offset:16896
	ds_read_b64 v[12:13], v223 offset:17408
	ds_read_b64 v[14:15], v223 offset:17920
	s_waitcnt lgkmcnt(8)
	v_mul_f32_e32 v227, v3, v17
	v_fma_f32 v242, v2, v16, v227
	v_mul_f32_e32 v227, v2, v17
	v_fma_f32 v243, v3, v16, -v227
	v_mul_f32_e32 v227, v5, v19
	v_fma_f32 v244, v4, v18, v227
	v_mul_f32_e32 v227, v4, v19
	v_fma_f32 v245, v5, v18, -v227
	v_mul_f32_e32 v227, v7, v21
	v_fma_f32 v246, v6, v20, v227
	v_mul_f32_e32 v227, v6, v21
	v_fma_f32 v247, v7, v20, -v227
	v_add_f32_e32 v22, v0, v244
	v_sub_f32_e32 v24, v0, v244
	v_add_f32_e32 v26, v242, v246
	v_sub_f32_e32 v28, v242, v246
	v_add_f32_e32 v23, v1, v245
	v_sub_f32_e32 v25, v1, v245
	v_add_f32_e32 v27, v243, v247
	v_sub_f32_e32 v29, v243, v247
	v_add_f32_e32 v80, v22, v26
	v_add_f32_e32 v81, v23, v27
	ds_write_b64 v223, v[80:81] offset:0
	v_sub_f32_e32 v82, v24, v29
	v_add_f32_e32 v83, v25, v28
	ds_write_b64 v223, v[82:83] offset:512
	v_sub_f32_e32 v84, v22, v26
	v_sub_f32_e32 v85, v23, v27
	ds_write_b64 v223, v[84:85] offset:1024
	v_add_f32_e32 v236, v24, v29
	v_sub_f32_e32 v237, v25, v28
	ds_write_b64 v223, v[236:237] offset:1536
	ds_read_b64 v[0:1], v223 offset:32768
	ds_read_b64 v[2:3], v223 offset:33280
	ds_read_b64 v[4:5], v223 offset:33792
	ds_read_b64 v[6:7], v223 offset:34304
	s_waitcnt lgkmcnt(8)
; HD float2 cmul(float2 a, float2 b){ return make_float2(a.x*b.x - a.y*b.y, a.x*b.y + a.y*b.x); }
; HD float2 cmulc(float2 a, float2 b){ return make_float2(a.x*b.x + a.y*b.y, a.y*b.x - a.x*b.y); }
; template<bool INV, bool NOTW>
; HD void bf4c(float2* Z, int i0, int i1, int i2, int i3, float2 w1, float2 w2, float2 w3){
;   float2 a0=Z[i0], a1=Z[i1], a2=Z[i2], a3=Z[i3];
;   if (INV && !NOTW){ a1=cmulc(a1,w1); a2=cmulc(a2,w2); a3=cmulc(a3,w3); }
;   float2 s02=make_float2(a0.x+a2.x,a0.y+a2.y), d02=make_float2(a0.x-a2.x,a0.y-a2.y);
;   float2 s13=make_float2(a1.x+a3.x,a1.y+a3.y), d13=make_float2(a1.x-a3.x,a1.y-a3.y);
;   float2 y0=make_float2(s02.x+s13.x,s02.y+s13.y), y2=make_float2(s02.x-s13.x,s02.y-s13.y);
;   float2 ym=make_float2(d02.x+d13.y,d02.y-d13.x);
;   float2 yp=make_float2(d02.x-d13.y,d02.y+d13.x);
;   float2 y1, y3;
;   if (INV){ y1=yp; y3=ym; } else if (NOTW){ y1=ym; y3=yp; } else { y1=cmul(ym,w1); y2=cmul(y2,w2); y3=cmul(yp,w3); }
;   Z[i0]=y0; Z[i1]=y1; Z[i2]=y2; Z[i3]=y3;
; }
; template<bool INV, int LQ, bool BARRIER=true>
; HD void fft_pass(float2* Z, const float2* twA, const float2* twB, int tid){
;     ...
;   } else {
;     int j=tid&(q-1); int base0=((tid>>LQ)<<(LQ+2))+j;
;     float2 w1=make_float2(1.f,0.f), w2=w1, w3=w1;
;     if (LQ>0){ int k=j*tws; w1=cmul(twA[k>>6],twB[k&63]); w2=cmul(w1,w1); w3=cmul(w2,w1); }
;     _Pragma("unroll") for (int i=0;i<8;++i){ int base=base0+i*2048; bf4c<INV,(LQ==0)>(Z,base,base+q,base+2*q,base+3*q,w1,w2,w3); }
;   }
;   if (BARRIER) __syncthreads(); else asm volatile("s_waitcnt lgkmcnt(0)" ::: "memory");
	v_mul_f32_e32 v227, v11, v17
	v_fma_f32 v242, v10, v16, v227
	v_mul_f32_e32 v227, v10, v17
	v_fma_f32 v243, v11, v16, -v227
	v_mul_f32_e32 v227, v13, v19
	v_fma_f32 v244, v12, v18, v227
	v_mul_f32_e32 v227, v12, v19
	v_fma_f32 v245, v13, v18, -v227
	v_mul_f32_e32 v227, v15, v21
	v_fma_f32 v246, v14, v20, v227
	v_mul_f32_e32 v227, v14, v21
	v_fma_f32 v247, v15, v20, -v227
	v_add_f32_e32 v22, v8, v244
	v_sub_f32_e32 v24, v8, v244
	v_add_f32_e32 v26, v242, v246
	v_sub_f32_e32 v28, v242, v246
	v_add_f32_e32 v23, v9, v245
	v_sub_f32_e32 v25, v9, v245
	v_add_f32_e32 v27, v243, v247
	v_sub_f32_e32 v29, v243, v247
	v_add_f32_e32 v80, v22, v26
	v_add_f32_e32 v81, v23, v27
	ds_write_b64 v223, v[80:81] offset:16384
	v_sub_f32_e32 v82, v24, v29
	v_add_f32_e32 v83, v25, v28
	ds_write_b64 v223, v[82:83] offset:16896
	v_sub_f32_e32 v84, v22, v26
	v_sub_f32_e32 v85, v23, v27
	ds_write_b64 v223, v[84:85] offset:17408
	v_add_f32_e32 v236, v24, v29
	v_sub_f32_e32 v237, v25, v28
	ds_write_b64 v223, v[236:237] offset:17920
	ds_read_b64 v[8:9], v223 offset:49152
	ds_read_b64 v[10:11], v223 offset:49664
	ds_read_b64 v[12:13], v223 offset:50176
	ds_read_b64 v[14:15], v223 offset:50688
	s_waitcnt lgkmcnt(8)
	v_mul_f32_e32 v227, v3, v17
	v_fma_f32 v242, v2, v16, v227
	v_mul_f32_e32 v227, v2, v17
	v_fma_f32 v243, v3, v16, -v227
	v_mul_f32_e32 v227, v5, v19
	v_fma_f32 v244, v4, v18, v227
	v_mul_f32_e32 v227, v4, v19
	v_fma_f32 v245, v5, v18, -v227
	v_mul_f32_e32 v227, v7, v21
	v_fma_f32 v246, v6, v20, v227
	v_mul_f32_e32 v227, v6, v21
	v_fma_f32 v247, v7, v20, -v227
	v_add_f32_e32 v22, v0, v244
	v_sub_f32_e32 v24, v0, v244
	v_add_f32_e32 v26, v242, v246
	v_sub_f32_e32 v28, v242, v246
	v_add_f32_e32 v23, v1, v245
	v_sub_f32_e32 v25, v1, v245
	v_add_f32_e32 v27, v243, v247
	v_sub_f32_e32 v29, v243, v247
	v_add_f32_e32 v80, v22, v26
	v_add_f32_e32 v81, v23, v27
	ds_write_b64 v223, v[80:81] offset:32768
	v_sub_f32_e32 v82, v24, v29
	v_add_f32_e32 v83, v25, v28
	ds_write_b64 v223, v[82:83] offset:33280
	v_sub_f32_e32 v84, v22, v26
	v_sub_f32_e32 v85, v23, v27
	ds_write_b64 v223, v[84:85] offset:33792
	v_add_f32_e32 v236, v24, v29
	v_sub_f32_e32 v237, v25, v28
	ds_write_b64 v223, v[236:237] offset:34304
	s_waitcnt lgkmcnt(4)
	v_mul_f32_e32 v227, v11, v17
	v_fma_f32 v242, v10, v16, v227
	v_mul_f32_e32 v227, v10, v17
	v_fma_f32 v243, v11, v16, -v227
	v_mul_f32_e32 v227, v13, v19
	v_fma_f32 v244, v12, v18, v227
	v_mul_f32_e32 v227, v12, v19
	v_fma_f32 v245, v13, v18, -v227
	v_mul_f32_e32 v227, v15, v21
	v_fma_f32 v246, v14, v20, v227
	v_mul_f32_e32 v227, v14, v21
	v_fma_f32 v247, v15, v20, -v227
	v_add_f32_e32 v22, v8, v244
	v_sub_f32_e32 v24, v8, v244
	v_add_f32_e32 v26, v242, v246
	v_sub_f32_e32 v28, v242, v246
	v_add_f32_e32 v23, v9, v245
	v_sub_f32_e32 v25, v9, v245
	v_add_f32_e32 v27, v243, v247
	v_sub_f32_e32 v29, v243, v247
	v_add_f32_e32 v80, v22, v26
	v_add_f32_e32 v81, v23, v27
	ds_write_b64 v223, v[80:81] offset:49152
	v_sub_f32_e32 v82, v24, v29
	v_add_f32_e32 v83, v25, v28
	ds_write_b64 v223, v[82:83] offset:49664
	v_sub_f32_e32 v84, v22, v26
	v_sub_f32_e32 v85, v23, v27
	ds_write_b64 v223, v[84:85] offset:50176
	v_add_f32_e32 v236, v24, v29
	v_sub_f32_e32 v237, v25, v28
	ds_write_b64 v223, v[236:237] offset:50688
	s_waitcnt lgkmcnt(0)
	s_barrier
	v_and_b32_e32 v226, 255, v154
	v_lshrrev_b32_e32 v224, 2, v226
	v_lshlrev_b32_e32 v224, 3, v224
	v_add_u32_e32 v224, 0x20800, v224
	v_and_b32_e32 v225, 3, v226
	v_lshlrev_b32_e32 v225, 7, v225
	v_add_u32_e32 v225, 0x20a00, v225
	ds_read_b64 v[238:239], v224
	ds_read_b64 v[240:241], v225
	s_waitcnt lgkmcnt(0)
	v_mul_f32_e32 v227, v239, v241
	v_fma_f32 v16, v238, v240, -v227
	v_mul_f32_e32 v227, v239, v240
	v_fma_f32 v17, v238, v241, v227
	v_mul_f32_e32 v227, v17, v17
	v_fma_f32 v18, v16, v16, -v227
	v_mul_f32_e32 v227, v17, v16
	v_fma_f32 v19, v16, v17, v227
	v_mul_f32_e32 v227, v19, v17
	v_fma_f32 v20, v18, v16, -v227
	v_mul_f32_e32 v227, v19, v16
	v_fma_f32 v21, v18, v17, v227
	v_lshrrev_b32_e32 v222, 8, v154
	v_lshlrev_b32_e32 v222, 10, v222
	v_add_u32_e32 v222, v222, v226
	v_lshlrev_b32_e32 v222, 3, v222
	v_add_u32_e32 v223, 0x10000, v222
	ds_read_b64 v[0:1], v222 offset:0
	ds_read_b64 v[2:3], v222 offset:2048
	ds_read_b64 v[4:5], v222 offset:4096
	ds_read_b64 v[6:7], v222 offset:6144
	ds_read_b64 v[8:9], v222 offset:16384
	ds_read_b64 v[10:11], v222 offset:18432
	ds_read_b64 v[12:13], v222 offset:20480
	ds_read_b64 v[14:15], v222 offset:22528
	s_waitcnt lgkmcnt(4)
	v_mul_f32_e32 v227, v3, v17
	v_fma_f32 v242, v2, v16, v227
	v_mul_f32_e32 v227, v2, v17
	v_fma_f32 v243, v3, v16, -v227
	v_mul_f32_e32 v227, v5, v19
	v_fma_f32 v244, v4, v18, v227
	v_mul_f32_e32 v227, v4, v19
	v_fma_f32 v245, v5, v18, -v227
	v_mul_f32_e32 v227, v7, v21
	v_fma_f32 v246, v6, v20, v227
	v_mul_f32_e32 v227, v6, v21
	v_fma_f32 v247, v7, v20, -v227
	v_add_f32_e32 v22, v0, v244
	v_sub_f32_e32 v24, v0, v244
	v_add_f32_e32 v26, v242, v246
	v_sub_f32_e32 v28, v242, v246
	v_add_f32_e32 v23, v1, v245
	v_sub_f32_e32 v25, v1, v245
	v_add_f32_e32 v27, v243, v247
	v_sub_f32_e32 v29, v243, v247
	v_add_f32_e32 v80, v22, v26
	v_add_f32_e32 v81, v23, v27
	ds_write_b64 v222, v[80:81] offset:0
	v_sub_f32_e32 v82, v24, v29
	v_add_f32_e32 v83, v25, v28
	ds_write_b64 v222, v[82:83] offset:2048
	v_sub_f32_e32 v84, v22, v26
	v_sub_f32_e32 v85, v23, v27
	ds_write_b64 v222, v[84:85] offset:4096
	v_add_f32_e32 v236, v24, v29
	v_sub_f32_e32 v237, v25, v28
	ds_write_b64 v222, v[236:237] offset:6144
	ds_read_b64 v[0:1], v222 offset:32768
	ds_read_b64 v[2:3], v222 offset:34816
	ds_read_b64 v[4:5], v222 offset:36864
	ds_read_b64 v[6:7], v222 offset:38912
	s_waitcnt lgkmcnt(8)
; HD float2 cmul(float2 a, float2 b){ return make_float2(a.x*b.x - a.y*b.y, a.x*b.y + a.y*b.x); }
; HD float2 cmulc(float2 a, float2 b){ return make_float2(a.x*b.x + a.y*b.y, a.y*b.x - a.x*b.y); }
; template<bool INV, bool NOTW>
; HD void bf4c(float2* Z, int i0, int i1, int i2, int i3, float2 w1, float2 w2, float2 w3){
;   float2 a0=Z[i0], a1=Z[i1], a2=Z[i2], a3=Z[i3];
;   if (INV && !NOTW){ a1=cmulc(a1,w1); a2=cmulc(a2,w2); a3=cmulc(a3,w3); }
;   float2 s02=make_float2(a0.x+a2.x,a0.y+a2.y), d02=make_float2(a0.x-a2.x,a0.y-a2.y);
;   float2 s13=make_float2(a1.x+a3.x,a1.y+a3.y), d13=make_float2(a1.x-a3.x,a1.y-a3.y);
;   float2 y0=make_float2(s02.x+s13.x,s02.y+s13.y), y2=make_float2(s02.x-s13.x,s02.y-s13.y);
;   float2 ym=make_float2(d02.x+d13.y,d02.y-d13.x);
;   float2 yp=make_float2(d02.x-d13.y,d02.y+d13.x);
;   float2 y1, y3;
;   if (INV){ y1=yp; y3=ym; } else if (NOTW){ y1=ym; y3=yp; } else { y1=cmul(ym,w1); y2=cmul(y2,w2); y3=cmul(yp,w3); }
;   Z[i0]=y0; Z[i1]=y1; Z[i2]=y2; Z[i3]=y3;
; }
; template<bool INV, int LQ, bool BARRIER=true>
; HD void fft_pass(float2* Z, const float2* twA, const float2* twB, int tid){
;     ...
;   } else {
;     int j=tid&(q-1); int base0=((tid>>LQ)<<(LQ+2))+j;
;     float2 w1=make_float2(1.f,0.f), w2=w1, w3=w1;
;     if (LQ>0){ int k=j*tws; w1=cmul(twA[k>>6],twB[k&63]); w2=cmul(w1,w1); w3=cmul(w2,w1); }
;     _Pragma("unroll") for (int i=0;i<8;++i){ int base=base0+i*2048; bf4c<INV,(LQ==0)>(Z,base,base+q,base+2*q,base+3*q,w1,w2,w3); }
;   }
;   if (BARRIER) __syncthreads(); else asm volatile("s_waitcnt lgkmcnt(0)" ::: "memory");
	v_mul_f32_e32 v227, v11, v17
	v_fma_f32 v242, v10, v16, v227
	v_mul_f32_e32 v227, v10, v17
	v_fma_f32 v243, v11, v16, -v227
	v_mul_f32_e32 v227, v13, v19
	v_fma_f32 v244, v12, v18, v227
	v_mul_f32_e32 v227, v12, v19
	v_fma_f32 v245, v13, v18, -v227
	v_mul_f32_e32 v227, v15, v21
	v_fma_f32 v246, v14, v20, v227
	v_mul_f32_e32 v227, v14, v21
	v_fma_f32 v247, v15, v20, -v227
	v_add_f32_e32 v22, v8, v244
	v_sub_f32_e32 v24, v8, v244
	v_add_f32_e32 v26, v242, v246
	v_sub_f32_e32 v28, v242, v246
	v_add_f32_e32 v23, v9, v245
	v_sub_f32_e32 v25, v9, v245
	v_add_f32_e32 v27, v243, v247
	v_sub_f32_e32 v29, v243, v247
	v_add_f32_e32 v80, v22, v26
	v_add_f32_e32 v81, v23, v27
	ds_write_b64 v222, v[80:81] offset:16384
	v_sub_f32_e32 v82, v24, v29
	v_add_f32_e32 v83, v25, v28
	ds_write_b64 v222, v[82:83] offset:18432
	v_sub_f32_e32 v84, v22, v26
	v_sub_f32_e32 v85, v23, v27
	ds_write_b64 v222, v[84:85] offset:20480
	v_add_f32_e32 v236, v24, v29
	v_sub_f32_e32 v237, v25, v28
	ds_write_b64 v222, v[236:237] offset:22528
	ds_read_b64 v[8:9], v222 offset:49152
	ds_read_b64 v[10:11], v222 offset:51200
	ds_read_b64 v[12:13], v222 offset:53248
	ds_read_b64 v[14:15], v222 offset:55296
	s_waitcnt lgkmcnt(8)
	v_mul_f32_e32 v227, v3, v17
	v_fma_f32 v242, v2, v16, v227
	v_mul_f32_e32 v227, v2, v17
	v_fma_f32 v243, v3, v16, -v227
	v_mul_f32_e32 v227, v5, v19
	v_fma_f32 v244, v4, v18, v227
	v_mul_f32_e32 v227, v4, v19
	v_fma_f32 v245, v5, v18, -v227
	v_mul_f32_e32 v227, v7, v21
	v_fma_f32 v246, v6, v20, v227
	v_mul_f32_e32 v227, v6, v21
	v_fma_f32 v247, v7, v20, -v227
	v_add_f32_e32 v22, v0, v244
	v_sub_f32_e32 v24, v0, v244
	v_add_f32_e32 v26, v242, v246
	v_sub_f32_e32 v28, v242, v246
	v_add_f32_e32 v23, v1, v245
	v_sub_f32_e32 v25, v1, v245
	v_add_f32_e32 v27, v243, v247
	v_sub_f32_e32 v29, v243, v247
	v_add_f32_e32 v80, v22, v26
	v_add_f32_e32 v81, v23, v27
	ds_write_b64 v222, v[80:81] offset:32768
	v_sub_f32_e32 v82, v24, v29
	v_add_f32_e32 v83, v25, v28
	ds_write_b64 v222, v[82:83] offset:34816
	v_sub_f32_e32 v84, v22, v26
	v_sub_f32_e32 v85, v23, v27
	ds_write_b64 v222, v[84:85] offset:36864
	v_add_f32_e32 v236, v24, v29
	v_sub_f32_e32 v237, v25, v28
	ds_write_b64 v222, v[236:237] offset:38912
	ds_read_b64 v[0:1], v223 offset:0
	ds_read_b64 v[2:3], v223 offset:2048
	ds_read_b64 v[4:5], v223 offset:4096
	ds_read_b64 v[6:7], v223 offset:6144
	s_waitcnt lgkmcnt(8)
	v_mul_f32_e32 v227, v11, v17
	v_fma_f32 v242, v10, v16, v227
	v_mul_f32_e32 v227, v10, v17
	v_fma_f32 v243, v11, v16, -v227
	v_mul_f32_e32 v227, v13, v19
	v_fma_f32 v244, v12, v18, v227
	v_mul_f32_e32 v227, v12, v19
	v_fma_f32 v245, v13, v18, -v227
	v_mul_f32_e32 v227, v15, v21
	v_fma_f32 v246, v14, v20, v227
	v_mul_f32_e32 v227, v14, v21
	v_fma_f32 v247, v15, v20, -v227
	v_add_f32_e32 v22, v8, v244
	v_sub_f32_e32 v24, v8, v244
	v_add_f32_e32 v26, v242, v246
	v_sub_f32_e32 v28, v242, v246
	v_add_f32_e32 v23, v9, v245
	v_sub_f32_e32 v25, v9, v245
	v_add_f32_e32 v27, v243, v247
	v_sub_f32_e32 v29, v243, v247
	v_add_f32_e32 v80, v22, v26
	v_add_f32_e32 v81, v23, v27
	ds_write_b64 v222, v[80:81] offset:49152
	v_sub_f32_e32 v82, v24, v29
	v_add_f32_e32 v83, v25, v28
	ds_write_b64 v222, v[82:83] offset:51200
	v_sub_f32_e32 v84, v22, v26
	v_sub_f32_e32 v85, v23, v27
	ds_write_b64 v222, v[84:85] offset:53248
	v_add_f32_e32 v236, v24, v29
	v_sub_f32_e32 v237, v25, v28
	ds_write_b64 v222, v[236:237] offset:55296
	ds_read_b64 v[8:9], v223 offset:16384
	ds_read_b64 v[10:11], v223 offset:18432
	ds_read_b64 v[12:13], v223 offset:20480
	ds_read_b64 v[14:15], v223 offset:22528
	s_waitcnt lgkmcnt(8)
	v_mul_f32_e32 v227, v3, v17
	v_fma_f32 v242, v2, v16, v227
	v_mul_f32_e32 v227, v2, v17
	v_fma_f32 v243, v3, v16, -v227
	v_mul_f32_e32 v227, v5, v19
	v_fma_f32 v244, v4, v18, v227
	v_mul_f32_e32 v227, v4, v19
	v_fma_f32 v245, v5, v18, -v227
	v_mul_f32_e32 v227, v7, v21
	v_fma_f32 v246, v6, v20, v227
	v_mul_f32_e32 v227, v6, v21
	v_fma_f32 v247, v7, v20, -v227
	v_add_f32_e32 v22, v0, v244
	v_sub_f32_e32 v24, v0, v244
	v_add_f32_e32 v26, v242, v246
	v_sub_f32_e32 v28, v242, v246
	v_add_f32_e32 v23, v1, v245
	v_sub_f32_e32 v25, v1, v245
	v_add_f32_e32 v27, v243, v247
	v_sub_f32_e32 v29, v243, v247
	v_add_f32_e32 v80, v22, v26
	v_add_f32_e32 v81, v23, v27
	ds_write_b64 v223, v[80:81] offset:0
	v_sub_f32_e32 v82, v24, v29
	v_add_f32_e32 v83, v25, v28
	ds_write_b64 v223, v[82:83] offset:2048
	v_sub_f32_e32 v84, v22, v26
	v_sub_f32_e32 v85, v23, v27
	ds_write_b64 v223, v[84:85] offset:4096
	v_add_f32_e32 v236, v24, v29
	v_sub_f32_e32 v237, v25, v28
	ds_write_b64 v223, v[236:237] offset:6144
	ds_read_b64 v[0:1], v223 offset:32768
	ds_read_b64 v[2:3], v223 offset:34816
	ds_read_b64 v[4:5], v223 offset:36864
	ds_read_b64 v[6:7], v223 offset:38912
	s_waitcnt lgkmcnt(8)
	v_mul_f32_e32 v227, v11, v17
	v_fma_f32 v242, v10, v16, v227
	v_mul_f32_e32 v227, v10, v17
	v_fma_f32 v243, v11, v16, -v227
	v_mul_f32_e32 v227, v13, v19
	v_fma_f32 v244, v12, v18, v227
	v_mul_f32_e32 v227, v12, v19
	v_fma_f32 v245, v13, v18, -v227
	v_mul_f32_e32 v227, v15, v21
	v_fma_f32 v246, v14, v20, v227
	v_mul_f32_e32 v227, v14, v21
	v_fma_f32 v247, v15, v20, -v227
	v_add_f32_e32 v22, v8, v244
	v_sub_f32_e32 v24, v8, v244
	v_add_f32_e32 v26, v242, v246
	v_sub_f32_e32 v28, v242, v246
	v_add_f32_e32 v23, v9, v245
	v_sub_f32_e32 v25, v9, v245
	v_add_f32_e32 v27, v243, v247
	v_sub_f32_e32 v29, v243, v247
	v_add_f32_e32 v80, v22, v26
	v_add_f32_e32 v81, v23, v27
	ds_write_b64 v223, v[80:81] offset:16384
	v_sub_f32_e32 v82, v24, v29
	v_add_f32_e32 v83, v25, v28
	ds_write_b64 v223, v[82:83] offset:18432
	v_sub_f32_e32 v84, v22, v26
	v_sub_f32_e32 v85, v23, v27
	ds_write_b64 v223, v[84:85] offset:20480
	v_add_f32_e32 v236, v24, v29
	v_sub_f32_e32 v237, v25, v28
	ds_write_b64 v223, v[236:237] offset:22528
	ds_read_b64 v[8:9], v223 offset:49152
	ds_read_b64 v[10:11], v223 offset:51200
	ds_read_b64 v[12:13], v223 offset:53248
	ds_read_b64 v[14:15], v223 offset:55296
	s_waitcnt lgkmcnt(8)
; HD float2 cmul(float2 a, float2 b){ return make_float2(a.x*b.x - a.y*b.y, a.x*b.y + a.y*b.x); }
; HD float2 cmulc(float2 a, float2 b){ return make_float2(a.x*b.x + a.y*b.y, a.y*b.x - a.x*b.y); }
; template<bool INV, bool NOTW>
; HD void bf4c(float2* Z, int i0, int i1, int i2, int i3, float2 w1, float2 w2, float2 w3){
;   float2 a0=Z[i0], a1=Z[i1], a2=Z[i2], a3=Z[i3];
;   if (INV && !NOTW){ a1=cmulc(a1,w1); a2=cmulc(a2,w2); a3=cmulc(a3,w3); }
;   float2 s02=make_float2(a0.x+a2.x,a0.y+a2.y), d02=make_float2(a0.x-a2.x,a0.y-a2.y);
;   float2 s13=make_float2(a1.x+a3.x,a1.y+a3.y), d13=make_float2(a1.x-a3.x,a1.y-a3.y);
;   float2 y0=make_float2(s02.x+s13.x,s02.y+s13.y), y2=make_float2(s02.x-s13.x,s02.y-s13.y);
;   float2 ym=make_float2(d02.x+d13.y,d02.y-d13.x);
;   float2 yp=make_float2(d02.x-d13.y,d02.y+d13.x);
;   float2 y1, y3;
;   if (INV){ y1=yp; y3=ym; } else if (NOTW){ y1=ym; y3=yp; } else { y1=cmul(ym,w1); y2=cmul(y2,w2); y3=cmul(yp,w3); }
;   Z[i0]=y0; Z[i1]=y1; Z[i2]=y2; Z[i3]=y3;
; }
; template<bool INV, int LQ, bool BARRIER=true>
; HD void fft_pass(float2* Z, const float2* twA, const float2* twB, int tid){
;     ...
;   } else if (LQ==10){
;     _Pragma("unroll") for (int e=0;e<2;++e){ int j=tid+512*e; int k=j*tws;
;       float2 w1=cmul(twA[k>>6],twB[k&63]), w2=cmul(w1,w1), w3=cmul(w2,w1);
;       _Pragma("unroll") for (int ip=0;ip<4;++ip){ int base=ip*4096+j; bf4c<INV,false>(Z,base,base+q,base+2*q,base+3*q,w1,w2,w3); } }
;   } else {
;     int j=tid&(q-1); int base0=((tid>>LQ)<<(LQ+2))+j;
;     float2 w1=make_float2(1.f,0.f), w2=w1, w3=w1;
;     if (LQ>0){ int k=j*tws; w1=cmul(twA[k>>6],twB[k&63]); w2=cmul(w1,w1); w3=cmul(w2,w1); }
;     _Pragma("unroll") for (int i=0;i<8;++i){ int base=base0+i*2048; bf4c<INV,(LQ==0)>(Z,base,base+q,base+2*q,base+3*q,w1,w2,w3); }
;   }
;   if (BARRIER) __syncthreads(); else asm volatile("s_waitcnt lgkmcnt(0)" ::: "memory");
	v_mul_f32_e32 v227, v3, v17
	v_fma_f32 v242, v2, v16, v227
	v_mul_f32_e32 v227, v2, v17
	v_fma_f32 v243, v3, v16, -v227
	v_mul_f32_e32 v227, v5, v19
	v_fma_f32 v244, v4, v18, v227
	v_mul_f32_e32 v227, v4, v19
	v_fma_f32 v245, v5, v18, -v227
	v_mul_f32_e32 v227, v7, v21
	v_fma_f32 v246, v6, v20, v227
	v_mul_f32_e32 v227, v6, v21
	v_fma_f32 v247, v7, v20, -v227
	v_add_f32_e32 v22, v0, v244
	v_sub_f32_e32 v24, v0, v244
	v_add_f32_e32 v26, v242, v246
	v_sub_f32_e32 v28, v242, v246
	v_add_f32_e32 v23, v1, v245
	v_sub_f32_e32 v25, v1, v245
	v_add_f32_e32 v27, v243, v247
	v_sub_f32_e32 v29, v243, v247
	v_add_f32_e32 v80, v22, v26
	v_add_f32_e32 v81, v23, v27
	ds_write_b64 v223, v[80:81] offset:32768
	v_sub_f32_e32 v82, v24, v29
	v_add_f32_e32 v83, v25, v28
	ds_write_b64 v223, v[82:83] offset:34816
	v_sub_f32_e32 v84, v22, v26
	v_sub_f32_e32 v85, v23, v27
	ds_write_b64 v223, v[84:85] offset:36864
	v_add_f32_e32 v236, v24, v29
	v_sub_f32_e32 v237, v25, v28
	ds_write_b64 v223, v[236:237] offset:38912
	s_waitcnt lgkmcnt(4)
	v_mul_f32_e32 v227, v11, v17
	v_fma_f32 v242, v10, v16, v227
	v_mul_f32_e32 v227, v10, v17
	v_fma_f32 v243, v11, v16, -v227
	v_mul_f32_e32 v227, v13, v19
	v_fma_f32 v244, v12, v18, v227
	v_mul_f32_e32 v227, v12, v19
	v_fma_f32 v245, v13, v18, -v227
	v_mul_f32_e32 v227, v15, v21
	v_fma_f32 v246, v14, v20, v227
	v_mul_f32_e32 v227, v14, v21
	v_fma_f32 v247, v15, v20, -v227
	v_add_f32_e32 v22, v8, v244
	v_sub_f32_e32 v24, v8, v244
	v_add_f32_e32 v26, v242, v246
	v_sub_f32_e32 v28, v242, v246
	v_add_f32_e32 v23, v9, v245
	v_sub_f32_e32 v25, v9, v245
	v_add_f32_e32 v27, v243, v247
	v_sub_f32_e32 v29, v243, v247
	v_add_f32_e32 v80, v22, v26
	v_add_f32_e32 v81, v23, v27
	ds_write_b64 v223, v[80:81] offset:49152
	v_sub_f32_e32 v82, v24, v29
	v_add_f32_e32 v83, v25, v28
	ds_write_b64 v223, v[82:83] offset:51200
	v_sub_f32_e32 v84, v22, v26
	v_sub_f32_e32 v85, v23, v27
	ds_write_b64 v223, v[84:85] offset:53248
	v_add_f32_e32 v236, v24, v29
	v_sub_f32_e32 v237, v25, v28
	ds_write_b64 v223, v[236:237] offset:55296
	s_waitcnt lgkmcnt(0)
	s_barrier
	v_add_u32_e32 v226, 0, v154
	v_lshrrev_b32_e32 v224, 4, v226
	v_lshlrev_b32_e32 v224, 3, v224
	v_add_u32_e32 v224, 0x20800, v224
	v_and_b32_e32 v225, 15, v226
	v_lshlrev_b32_e32 v225, 5, v225
	v_add_u32_e32 v225, 0x20a00, v225
	ds_read_b64 v[238:239], v224
	ds_read_b64 v[240:241], v225
	s_waitcnt lgkmcnt(0)
	v_mul_f32_e32 v227, v239, v241
	v_fma_f32 v16, v238, v240, -v227
	v_mul_f32_e32 v227, v239, v240
	v_fma_f32 v17, v238, v241, v227
	v_mul_f32_e32 v227, v17, v17
	v_fma_f32 v18, v16, v16, -v227
	v_mul_f32_e32 v227, v17, v16
	v_fma_f32 v19, v16, v17, v227
	v_mul_f32_e32 v227, v19, v17
	v_fma_f32 v20, v18, v16, -v227
	v_mul_f32_e32 v227, v19, v16
	v_fma_f32 v21, v18, v17, v227
	v_lshlrev_b32_e32 v222, 3, v154
	v_add_u32_e32 v223, 0x10000, v222
	ds_read_b64 v[0:1], v222 offset:0
	ds_read_b64 v[2:3], v222 offset:8192
	ds_read_b64 v[4:5], v222 offset:16384
	ds_read_b64 v[6:7], v222 offset:24576
	ds_read_b64 v[8:9], v222 offset:32768
	ds_read_b64 v[10:11], v222 offset:40960
	ds_read_b64 v[12:13], v222 offset:49152
	ds_read_b64 v[14:15], v222 offset:57344
	s_waitcnt lgkmcnt(4)
	v_mul_f32_e32 v227, v3, v17
	v_fma_f32 v242, v2, v16, v227
	v_mul_f32_e32 v227, v2, v17
	v_fma_f32 v243, v3, v16, -v227
	v_mul_f32_e32 v227, v5, v19
	v_fma_f32 v244, v4, v18, v227
	v_mul_f32_e32 v227, v4, v19
	v_fma_f32 v245, v5, v18, -v227
	v_mul_f32_e32 v227, v7, v21
	v_fma_f32 v246, v6, v20, v227
	v_mul_f32_e32 v227, v6, v21
	v_fma_f32 v247, v7, v20, -v227
	v_add_f32_e32 v22, v0, v244
	v_sub_f32_e32 v24, v0, v244
	v_add_f32_e32 v26, v242, v246
	v_sub_f32_e32 v28, v242, v246
	v_add_f32_e32 v23, v1, v245
	v_sub_f32_e32 v25, v1, v245
	v_add_f32_e32 v27, v243, v247
	v_sub_f32_e32 v29, v243, v247
	v_add_f32_e32 v80, v22, v26
	v_add_f32_e32 v81, v23, v27
	ds_write_b64 v222, v[80:81] offset:0
	v_sub_f32_e32 v82, v24, v29
	v_add_f32_e32 v83, v25, v28
	ds_write_b64 v222, v[82:83] offset:8192
	v_sub_f32_e32 v84, v22, v26
	v_sub_f32_e32 v85, v23, v27
	ds_write_b64 v222, v[84:85] offset:16384
	v_add_f32_e32 v236, v24, v29
	v_sub_f32_e32 v237, v25, v28
	ds_write_b64 v222, v[236:237] offset:24576
	ds_read_b64 v[0:1], v223 offset:0
	ds_read_b64 v[2:3], v223 offset:8192
	ds_read_b64 v[4:5], v223 offset:16384
	ds_read_b64 v[6:7], v223 offset:24576
	s_waitcnt lgkmcnt(8)
	v_mul_f32_e32 v227, v11, v17
	v_fma_f32 v242, v10, v16, v227
	v_mul_f32_e32 v227, v10, v17
	v_fma_f32 v243, v11, v16, -v227
	v_mul_f32_e32 v227, v13, v19
	v_fma_f32 v244, v12, v18, v227
	v_mul_f32_e32 v227, v12, v19
	v_fma_f32 v245, v13, v18, -v227
	v_mul_f32_e32 v227, v15, v21
	v_fma_f32 v246, v14, v20, v227
	v_mul_f32_e32 v227, v14, v21
	v_fma_f32 v247, v15, v20, -v227
	v_add_f32_e32 v22, v8, v244
	v_sub_f32_e32 v24, v8, v244
	v_add_f32_e32 v26, v242, v246
	v_sub_f32_e32 v28, v242, v246
	v_add_f32_e32 v23, v9, v245
	v_sub_f32_e32 v25, v9, v245
	v_add_f32_e32 v27, v243, v247
	v_sub_f32_e32 v29, v243, v247
	v_add_f32_e32 v80, v22, v26
	v_add_f32_e32 v81, v23, v27
	ds_write_b64 v222, v[80:81] offset:32768
	v_sub_f32_e32 v82, v24, v29
	v_add_f32_e32 v83, v25, v28
	ds_write_b64 v222, v[82:83] offset:40960
	v_sub_f32_e32 v84, v22, v26
	v_sub_f32_e32 v85, v23, v27
	ds_write_b64 v222, v[84:85] offset:49152
	v_add_f32_e32 v236, v24, v29
	v_sub_f32_e32 v237, v25, v28
	ds_write_b64 v222, v[236:237] offset:57344
	ds_read_b64 v[8:9], v223 offset:32768
	ds_read_b64 v[10:11], v223 offset:40960
	ds_read_b64 v[12:13], v223 offset:49152
	ds_read_b64 v[14:15], v223 offset:57344
	s_waitcnt lgkmcnt(8)
; HD float2 cmul(float2 a, float2 b){ return make_float2(a.x*b.x - a.y*b.y, a.x*b.y + a.y*b.x); }
; HD float2 cmulc(float2 a, float2 b){ return make_float2(a.x*b.x + a.y*b.y, a.y*b.x - a.x*b.y); }
; template<bool INV, bool NOTW>
; HD void bf4c(float2* Z, int i0, int i1, int i2, int i3, float2 w1, float2 w2, float2 w3){
;   float2 a0=Z[i0], a1=Z[i1], a2=Z[i2], a3=Z[i3];
;   if (INV && !NOTW){ a1=cmulc(a1,w1); a2=cmulc(a2,w2); a3=cmulc(a3,w3); }
;   float2 s02=make_float2(a0.x+a2.x,a0.y+a2.y), d02=make_float2(a0.x-a2.x,a0.y-a2.y);
;   float2 s13=make_float2(a1.x+a3.x,a1.y+a3.y), d13=make_float2(a1.x-a3.x,a1.y-a3.y);
;   float2 y0=make_float2(s02.x+s13.x,s02.y+s13.y), y2=make_float2(s02.x-s13.x,s02.y-s13.y);
;   float2 ym=make_float2(d02.x+d13.y,d02.y-d13.x);
;   float2 yp=make_float2(d02.x-d13.y,d02.y+d13.x);
;   float2 y1, y3;
;   if (INV){ y1=yp; y3=ym; } else if (NOTW){ y1=ym; y3=yp; } else { y1=cmul(ym,w1); y2=cmul(y2,w2); y3=cmul(yp,w3); }
;   Z[i0]=y0; Z[i1]=y1; Z[i2]=y2; Z[i3]=y3;
; }
; template<bool INV, int LQ, bool BARRIER=true>
; HD void fft_pass(float2* Z, const float2* twA, const float2* twB, int tid){
;     ...
;   } else if (LQ==10){
;     _Pragma("unroll") for (int e=0;e<2;++e){ int j=tid+512*e; int k=j*tws;
;       float2 w1=cmul(twA[k>>6],twB[k&63]), w2=cmul(w1,w1), w3=cmul(w2,w1);
;       _Pragma("unroll") for (int ip=0;ip<4;++ip){ int base=ip*4096+j; bf4c<INV,false>(Z,base,base+q,base+2*q,base+3*q,w1,w2,w3); } }
	v_mul_f32_e32 v227, v3, v17
	v_fma_f32 v242, v2, v16, v227
	v_mul_f32_e32 v227, v2, v17
	v_fma_f32 v243, v3, v16, -v227
	v_mul_f32_e32 v227, v5, v19
	v_fma_f32 v244, v4, v18, v227
	v_mul_f32_e32 v227, v4, v19
	v_fma_f32 v245, v5, v18, -v227
	v_mul_f32_e32 v227, v7, v21
	v_fma_f32 v246, v6, v20, v227
	v_mul_f32_e32 v227, v6, v21
	v_fma_f32 v247, v7, v20, -v227
	v_add_f32_e32 v22, v0, v244
	v_sub_f32_e32 v24, v0, v244
	v_add_f32_e32 v26, v242, v246
	v_sub_f32_e32 v28, v242, v246
	v_add_f32_e32 v23, v1, v245
	v_sub_f32_e32 v25, v1, v245
	v_add_f32_e32 v27, v243, v247
	v_sub_f32_e32 v29, v243, v247
	v_add_f32_e32 v80, v22, v26
	v_add_f32_e32 v81, v23, v27
	ds_write_b64 v223, v[80:81] offset:0
	v_sub_f32_e32 v82, v24, v29
	v_add_f32_e32 v83, v25, v28
	ds_write_b64 v223, v[82:83] offset:8192
	v_sub_f32_e32 v84, v22, v26
	v_sub_f32_e32 v85, v23, v27
	ds_write_b64 v223, v[84:85] offset:16384
	v_add_f32_e32 v236, v24, v29
	v_sub_f32_e32 v237, v25, v28
	ds_write_b64 v223, v[236:237] offset:24576
	s_waitcnt lgkmcnt(4)
	v_mul_f32_e32 v227, v11, v17
	v_fma_f32 v242, v10, v16, v227
	v_mul_f32_e32 v227, v10, v17
	v_fma_f32 v243, v11, v16, -v227
	v_mul_f32_e32 v227, v13, v19
	v_fma_f32 v244, v12, v18, v227
	v_mul_f32_e32 v227, v12, v19
	v_fma_f32 v245, v13, v18, -v227
	v_mul_f32_e32 v227, v15, v21
	v_fma_f32 v246, v14, v20, v227
	v_mul_f32_e32 v227, v14, v21
	v_fma_f32 v247, v15, v20, -v227
	v_add_f32_e32 v22, v8, v244
	v_sub_f32_e32 v24, v8, v244
	v_add_f32_e32 v26, v242, v246
	v_sub_f32_e32 v28, v242, v246
	v_add_f32_e32 v23, v9, v245
	v_sub_f32_e32 v25, v9, v245
	v_add_f32_e32 v27, v243, v247
	v_sub_f32_e32 v29, v243, v247
	v_add_f32_e32 v80, v22, v26
	v_add_f32_e32 v81, v23, v27
	ds_write_b64 v223, v[80:81] offset:32768
	v_sub_f32_e32 v82, v24, v29
	v_add_f32_e32 v83, v25, v28
	ds_write_b64 v223, v[82:83] offset:40960
	v_sub_f32_e32 v84, v22, v26
	v_sub_f32_e32 v85, v23, v27
	ds_write_b64 v223, v[84:85] offset:49152
	v_add_f32_e32 v236, v24, v29
	v_sub_f32_e32 v237, v25, v28
	ds_write_b64 v223, v[236:237] offset:57344
	s_nop 0
	v_add_u32_e32 v226, 512, v154
	v_lshrrev_b32_e32 v224, 4, v226
	v_lshlrev_b32_e32 v224, 3, v224
	v_add_u32_e32 v224, 0x20800, v224
	v_and_b32_e32 v225, 15, v226
	v_lshlrev_b32_e32 v225, 5, v225
	v_add_u32_e32 v225, 0x20a00, v225
	ds_read_b64 v[238:239], v224
	ds_read_b64 v[240:241], v225
	s_waitcnt lgkmcnt(0)
	v_mul_f32_e32 v227, v239, v241
	v_fma_f32 v16, v238, v240, -v227
	v_mul_f32_e32 v227, v239, v240
	v_fma_f32 v17, v238, v241, v227
	v_mul_f32_e32 v227, v17, v17
	v_fma_f32 v18, v16, v16, -v227
	v_mul_f32_e32 v227, v17, v16
	v_fma_f32 v19, v16, v17, v227
	v_mul_f32_e32 v227, v19, v17
	v_fma_f32 v20, v18, v16, -v227
	v_mul_f32_e32 v227, v19, v16
	v_fma_f32 v21, v18, v17, v227
	ds_read_b64 v[0:1], v222 offset:4096
	ds_read_b64 v[2:3], v222 offset:12288
	ds_read_b64 v[4:5], v222 offset:20480
	ds_read_b64 v[6:7], v222 offset:28672
	ds_read_b64 v[8:9], v222 offset:36864
	ds_read_b64 v[10:11], v222 offset:45056
	ds_read_b64 v[12:13], v222 offset:53248
	ds_read_b64 v[14:15], v222 offset:61440
	s_waitcnt lgkmcnt(4)
	v_mul_f32_e32 v227, v3, v17
	v_fma_f32 v242, v2, v16, v227
	v_mul_f32_e32 v227, v2, v17
	v_fma_f32 v243, v3, v16, -v227
	v_mul_f32_e32 v227, v5, v19
	v_fma_f32 v244, v4, v18, v227
	v_mul_f32_e32 v227, v4, v19
	v_fma_f32 v245, v5, v18, -v227
	v_mul_f32_e32 v227, v7, v21
	v_fma_f32 v246, v6, v20, v227
	v_mul_f32_e32 v227, v6, v21
	v_fma_f32 v247, v7, v20, -v227
	v_add_f32_e32 v22, v0, v244
	v_sub_f32_e32 v24, v0, v244
	v_add_f32_e32 v26, v242, v246
	v_sub_f32_e32 v28, v242, v246
	v_add_f32_e32 v23, v1, v245
	v_sub_f32_e32 v25, v1, v245
	v_add_f32_e32 v27, v243, v247
	v_sub_f32_e32 v29, v243, v247
	v_add_f32_e32 v80, v22, v26
	v_add_f32_e32 v81, v23, v27
	ds_write_b64 v222, v[80:81] offset:4096
	v_sub_f32_e32 v82, v24, v29
	v_add_f32_e32 v83, v25, v28
	ds_write_b64 v222, v[82:83] offset:12288
	v_sub_f32_e32 v84, v22, v26
	v_sub_f32_e32 v85, v23, v27
	ds_write_b64 v222, v[84:85] offset:20480
	v_add_f32_e32 v236, v24, v29
	v_sub_f32_e32 v237, v25, v28
	ds_write_b64 v222, v[236:237] offset:28672
	ds_read_b64 v[0:1], v223 offset:4096
	ds_read_b64 v[2:3], v223 offset:12288
	ds_read_b64 v[4:5], v223 offset:20480
	ds_read_b64 v[6:7], v223 offset:28672
	s_waitcnt lgkmcnt(8)
; HD float2 cmul(float2 a, float2 b){ return make_float2(a.x*b.x - a.y*b.y, a.x*b.y + a.y*b.x); }
; HD float2 cmulc(float2 a, float2 b){ return make_float2(a.x*b.x + a.y*b.y, a.y*b.x - a.x*b.y); }
; template<bool INV, bool NOTW>
; HD void bf4c(float2* Z, int i0, int i1, int i2, int i3, float2 w1, float2 w2, float2 w3){
;   float2 a0=Z[i0], a1=Z[i1], a2=Z[i2], a3=Z[i3];
;   if (INV && !NOTW){ a1=cmulc(a1,w1); a2=cmulc(a2,w2); a3=cmulc(a3,w3); }
;   float2 s02=make_float2(a0.x+a2.x,a0.y+a2.y), d02=make_float2(a0.x-a2.x,a0.y-a2.y);
;   float2 s13=make_float2(a1.x+a3.x,a1.y+a3.y), d13=make_float2(a1.x-a3.x,a1.y-a3.y);
;   float2 y0=make_float2(s02.x+s13.x,s02.y+s13.y), y2=make_float2(s02.x-s13.x,s02.y-s13.y);
;   float2 ym=make_float2(d02.x+d13.y,d02.y-d13.x);
;   float2 yp=make_float2(d02.x-d13.y,d02.y+d13.x);
;   float2 y1, y3;
;   if (INV){ y1=yp; y3=ym; } else if (NOTW){ y1=ym; y3=yp; } else { y1=cmul(ym,w1); y2=cmul(y2,w2); y3=cmul(yp,w3); }
;   Z[i0]=y0; Z[i1]=y1; Z[i2]=y2; Z[i3]=y3;
; template<bool INV, int LQ, bool BARRIER=true>
; HD void fft_pass(float2* Z, const float2* twA, const float2* twB, int tid){
;     ...
;   } else if (LQ==10){
;     _Pragma("unroll") for (int e=0;e<2;++e){ int j=tid+512*e; int k=j*tws;
;       float2 w1=cmul(twA[k>>6],twB[k&63]), w2=cmul(w1,w1), w3=cmul(w2,w1);
;       _Pragma("unroll") for (int ip=0;ip<4;++ip){ int base=ip*4096+j; bf4c<INV,false>(Z,base,base+q,base+2*q,base+3*q,w1,w2,w3); } }
	v_mul_f32_e32 v227, v11, v17
	v_fma_f32 v242, v10, v16, v227
	v_mul_f32_e32 v227, v10, v17
	v_fma_f32 v243, v11, v16, -v227
	v_mul_f32_e32 v227, v13, v19
	v_fma_f32 v244, v12, v18, v227
	v_mul_f32_e32 v227, v12, v19
	v_fma_f32 v245, v13, v18, -v227
	v_mul_f32_e32 v227, v15, v21
	v_fma_f32 v246, v14, v20, v227
	v_mul_f32_e32 v227, v14, v21
	v_fma_f32 v247, v15, v20, -v227
	v_add_f32_e32 v22, v8, v244
	v_sub_f32_e32 v24, v8, v244
	v_add_f32_e32 v26, v242, v246
	v_sub_f32_e32 v28, v242, v246
	v_add_f32_e32 v23, v9, v245
	v_sub_f32_e32 v25, v9, v245
	v_add_f32_e32 v27, v243, v247
	v_sub_f32_e32 v29, v243, v247
	v_add_f32_e32 v80, v22, v26
	v_add_f32_e32 v81, v23, v27
	ds_write_b64 v222, v[80:81] offset:36864
	v_sub_f32_e32 v82, v24, v29
	v_add_f32_e32 v83, v25, v28
	ds_write_b64 v222, v[82:83] offset:45056
	v_sub_f32_e32 v84, v22, v26
	v_sub_f32_e32 v85, v23, v27
	ds_write_b64 v222, v[84:85] offset:53248
	v_add_f32_e32 v236, v24, v29
	v_sub_f32_e32 v237, v25, v28
	ds_write_b64 v222, v[236:237] offset:61440
	ds_read_b64 v[8:9], v223 offset:36864
	ds_read_b64 v[10:11], v223 offset:45056
	ds_read_b64 v[12:13], v223 offset:53248
	ds_read_b64 v[14:15], v223 offset:61440
	s_waitcnt lgkmcnt(8)
	v_mul_f32_e32 v227, v3, v17
	v_fma_f32 v242, v2, v16, v227
	v_mul_f32_e32 v227, v2, v17
	v_fma_f32 v243, v3, v16, -v227
	v_mul_f32_e32 v227, v5, v19
	v_fma_f32 v244, v4, v18, v227
	v_mul_f32_e32 v227, v4, v19
	v_fma_f32 v245, v5, v18, -v227
	v_mul_f32_e32 v227, v7, v21
	v_fma_f32 v246, v6, v20, v227
	v_mul_f32_e32 v227, v6, v21
	v_fma_f32 v247, v7, v20, -v227
	v_add_f32_e32 v22, v0, v244
	v_sub_f32_e32 v24, v0, v244
	v_add_f32_e32 v26, v242, v246
	v_sub_f32_e32 v28, v242, v246
	v_add_f32_e32 v23, v1, v245
	v_sub_f32_e32 v25, v1, v245
	v_add_f32_e32 v27, v243, v247
	v_sub_f32_e32 v29, v243, v247
	v_add_f32_e32 v80, v22, v26
	v_add_f32_e32 v81, v23, v27
	ds_write_b64 v223, v[80:81] offset:4096
	v_sub_f32_e32 v82, v24, v29
	v_add_f32_e32 v83, v25, v28
	ds_write_b64 v223, v[82:83] offset:12288
	v_sub_f32_e32 v84, v22, v26
	v_sub_f32_e32 v85, v23, v27
	ds_write_b64 v223, v[84:85] offset:20480
	v_add_f32_e32 v236, v24, v29
	v_sub_f32_e32 v237, v25, v28
	ds_write_b64 v223, v[236:237] offset:28672
	s_waitcnt lgkmcnt(4)
	v_mul_f32_e32 v227, v11, v17
	v_fma_f32 v242, v10, v16, v227
	v_mul_f32_e32 v227, v10, v17
	v_fma_f32 v243, v11, v16, -v227
	v_mul_f32_e32 v227, v13, v19
	v_fma_f32 v244, v12, v18, v227
	v_mul_f32_e32 v227, v12, v19
	v_fma_f32 v245, v13, v18, -v227
	v_mul_f32_e32 v227, v15, v21
	v_fma_f32 v246, v14, v20, v227
	v_mul_f32_e32 v227, v14, v21
	v_fma_f32 v247, v15, v20, -v227
	v_add_f32_e32 v22, v8, v244
	v_sub_f32_e32 v24, v8, v244
	v_add_f32_e32 v26, v242, v246
	v_sub_f32_e32 v28, v242, v246
	v_add_f32_e32 v23, v9, v245
	v_sub_f32_e32 v25, v9, v245
	v_add_f32_e32 v27, v243, v247
	v_sub_f32_e32 v29, v243, v247
	v_add_f32_e32 v80, v22, v26
	v_add_f32_e32 v81, v23, v27
	ds_write_b64 v223, v[80:81] offset:36864
	v_sub_f32_e32 v82, v24, v29
	v_add_f32_e32 v83, v25, v28
	ds_write_b64 v223, v[82:83] offset:45056
	v_sub_f32_e32 v84, v22, v26
	v_sub_f32_e32 v85, v23, v27
	ds_write_b64 v223, v[84:85] offset:53248
	v_add_f32_e32 v236, v24, v29
	v_sub_f32_e32 v237, v25, v28
	ds_write_b64 v223, v[236:237] offset:61440
	s_waitcnt lgkmcnt(0)
	s_barrier
	s_mov_b64 s[12:13], -1
	s_and_b64 vcc, exec, s[50:51]
	s_cbranch_vccz .LBB0_1340
	v_mov_b32_e32 v0, v86
	s_mov_b64 s[50:51], 0
	v_and_b32_e32 v1, 63, v0
	v_lshl_add_u32 v30, v1, 3, s91
	v_ashrrev_i32_e32 v1, 31, v0
	v_lshlrev_b64 v[6:7], 1, v[0:1]
	v_lshl_add_u64 v[2:3], v[76:77], 0, v[6:7]
	v_lshl_add_u64 v[4:5], s[14:15], 0, v[6:7]
	v_lshl_add_u64 v[6:7], s[54:55], 0, v[6:7]
	v_lshl_add_u32 v31, v0, 3, 0
